# v100 with the per-CU L1 invalidate moved to wave 1 (runs beside thread 0's barrier protocol, completes before the closing s_barrier); thread 0 of non-leader workgroups issues no cache op
# baseline (speedup 1.0000x reference)
.LBB0_63:
	s_or_b64 exec, exec, s[2:3]
	v_readfirstlane_b32 s99, v0
	s_nop 3
	s_lshr_b32 s99, s99, 6
	s_cmp_lg_u32 s99, 1
	s_cbranch_scc1 .Lbar_noinv_1
	buffer_inv sc1
	s_waitcnt vmcnt(0)
.Lbar_noinv_1:
	s_waitcnt lgkmcnt(0)
	s_barrier
.LBB0_64:
	v_mov_b32_e32 v1, v0
	s_load_dword s11, s[0:1], 0xe0
	s_mov_b32 s2, s10
	v_ashrrev_i32_e32 v2, 8, v1
	s_nop 0
	v_lshl_add_u32 v1, s2, 1, v2
	s_movk_i32 s2, 0x17f
	v_cmp_lt_i32_e32 vcc, s2, v1
	s_and_saveexec_b64 s[2:3], vcc
	s_xor_b64 s[2:3], exec, s[2:3]
	s_cbranch_execz .LBB0_107
	s_add_u32 s4, s16, 0xc0
	s_addc_u32 s5, s17, 0
	s_add_u32 s6, s16, 0xb8
	s_addc_u32 s7, s17, 0
	s_add_u32 s12, s16, 0xb0
	s_addc_u32 s13, s17, 0
	s_add_u32 s14, s16, 0xa8
	s_addc_u32 s15, s17, 0
	s_add_u32 s20, s16, 0x78
	s_addc_u32 s21, s17, 0
	s_add_u32 s22, s16, 0x70
	s_addc_u32 s23, s17, 0
	v_mul_lo_u32 v22, v1, 10
	s_add_u32 s24, s16, 0x58
	v_add_u32_e32 v23, 0xfffff100, v22
	s_addc_u32 s25, s17, 0
	s_mov_b32 s33, 0
	s_movk_i32 s52, 0x44f
	s_movk_i32 s53, 0x4af
	s_movk_i32 s54, 0x4ef
	s_movk_i32 s55, 0x6ef
	s_movk_i32 s56, 0xc6f
	s_movk_i32 s57, 0x11ef
	s_movk_i32 s58, 0x176f
	v_mov_b32_e32 v3, 0
	s_movk_i32 s59, 0x1c0
	s_branch .LBB0_69

.Lbar_noinv_2:
	s_waitcnt lgkmcnt(0)
	s_barrier
.LBB0_216:
	v_mov_b32_e32 v1, v0
	s_mov_b32 s2, s10
	v_ashrrev_i32_e32 v2, 8, v1
	s_movk_i32 s3, 0x800
	v_lshl_add_u32 v1, s2, 1, v2
	v_cmp_gt_i32_e32 vcc, s3, v1
	s_and_saveexec_b64 s[6:7], vcc
	s_cbranch_execz .LBB0_223
	s_load_dword s3, s[0:1], 0xe0
	s_load_dwordx2 s[12:13], s[16:17], 0xd0
	v_lshlrev_b32_e32 v2, 3, v2
	v_lshl_add_u32 v2, s2, 4, v2
	v_add_u32_e32 v37, 0xffffe000, v2
	s_waitcnt lgkmcnt(0)
	s_lshl_b32 s11, s3, 1
	s_add_u32 s8, s12, 0x4000
	v_mbcnt_lo_u32_b32 v2, -1, 0
	s_addc_u32 s9, s13, 0
	v_mbcnt_hi_u32_b32 v44, -1, v2
	s_add_u32 s12, s12, 0x17f0000
	v_and_b32_e32 v2, 64, v44
	s_addc_u32 s13, s13, 0
	s_lshl_b32 s21, s3, 4
	s_mov_b64 s[14:15], 0
	s_movk_i32 s26, 0x2000
	s_movk_i32 s27, 0x1fff
	v_mov_b32_e32 v35, 0
	s_movk_i32 s28, 0x1800
	s_movk_i32 s29, 0x1000
	v_add_u32_e32 v45, 64, v2
	v_xor_b32_e32 v46, 32, v44
	v_xor_b32_e32 v47, 16, v44
	v_xor_b32_e32 v48, 8, v44
	v_xor_b32_e32 v49, 4, v44
	v_xor_b32_e32 v50, 2, v44
	v_xor_b32_e32 v51, 1, v44
	s_mov_b32 s20, 0x3a800000
	v_mov_b32_e32 v36, 0x358637bd
	s_mov_b32 s30, 0x800000
	s_mov_b64 s[22:23], 0x1000
	s_movk_i32 s31, 0x7ff
	s_branch .LBB0_219

.Lbar_noinv_3:
	s_waitcnt lgkmcnt(0)
	s_barrier
.LBB0_281:
	s_mov_b32 s98, 0
	v_mov_b32_e32 v255, 0x0
	v_bfe_u32 v1, v0, 0, 1
	v_lshlrev_b32_e32 v1, 7, v1
	v_xor_b32_e32 v255, v255, v1
	v_bfe_u32 v1, v0, 1, 3
	v_mul_u32_u24_e32 v1, 0x110, v1
	v_xor_b32_e32 v255, v255, v1
	v_bfe_u32 v1, v0, 4, 2
	v_lshlrev_b32_e32 v1, 4, v1
	v_xor_b32_e32 v255, v255, v1
	v_bfe_u32 v1, v0, 8, 1
	v_lshlrev_b32_e32 v1, 14, v1
	v_xor_b32_e32 v255, v255, v1
	v_add_u32_e32 v254, 0x10000, v255
	v_xor_b32_e32 v253, 0x880, v255
	v_xor_b32_e32 v252, 0x10880, v255
	v_mov_b32_e32 v251, 0x8000
	v_bfe_u32 v1, v0, 1, 3
	v_lshlrev_b32_e32 v1, 8, v1
	v_add_u32_e32 v251, v251, v1
	v_bfe_u32 v1, v0, 6, 2
	v_mul_u32_u24_e32 v1, 0x1800, v1
	v_add_u32_e32 v251, v251, v1
	v_mov_b32_e32 v2, 0x0
	v_bfe_u32 v1, v0, 0, 1
	v_lshlrev_b32_e32 v1, 7, v1
	v_xor_b32_e32 v2, v2, v1
	v_bfe_u32 v1, v0, 1, 3
	v_lshlrev_b32_e32 v1, 4, v1
	v_xor_b32_e32 v2, v2, v1
	v_bfe_u32 v1, v0, 4, 2
	v_lshlrev_b32_e32 v1, 4, v1
	v_xor_b32_e32 v2, v2, v1
	v_bfe_u32 v1, v0, 6, 1
	v_lshlrev_b32_e32 v1, 7, v1
	v_xor_b32_e32 v2, v2, v1
	v_add_u32_e32 v251, v251, v2
	v_add_u32_e32 v250, 0x10000, v251
	v_mov_b32_e32 v249, 0x8800
	v_bfe_u32 v1, v0, 1, 3
	v_lshlrev_b32_e32 v1, 8, v1
	v_add_u32_e32 v249, v249, v1
	v_bfe_u32 v1, v0, 6, 2
	v_mul_u32_u24_e32 v1, 0x1800, v1
	v_add_u32_e32 v249, v249, v1
	v_mov_b32_e32 v2, 0x80
	v_bfe_u32 v1, v0, 0, 1
	v_lshlrev_b32_e32 v1, 7, v1
	v_xor_b32_e32 v2, v2, v1
	v_bfe_u32 v1, v0, 1, 3
	v_lshlrev_b32_e32 v1, 4, v1
	v_xor_b32_e32 v2, v2, v1
	v_bfe_u32 v1, v0, 4, 2
	v_lshlrev_b32_e32 v1, 4, v1
	v_xor_b32_e32 v2, v2, v1
	v_bfe_u32 v1, v0, 6, 1
	v_lshlrev_b32_e32 v1, 7, v1
	v_xor_b32_e32 v2, v2, v1
	v_add_u32_e32 v249, v249, v2
	v_add_u32_e32 v248, 0x10000, v249
	v_xor_b32_e32 v247, 0x40, v255
	v_xor_b32_e32 v246, 0x10040, v255
	v_xor_b32_e32 v245, 0x8c0, v255
	v_xor_b32_e32 v244, 0x108c0, v255
	v_xor_b32_e32 v243, 0x40, v251
	v_xor_b32_e32 v242, 0x10040, v251
	v_xor_b32_e32 v241, 0x40, v249
	v_xor_b32_e32 v240, 0x10040, v249
	v_mov_b32_e32 v239, 0x0
	v_bfe_u32 v1, v0, 0, 4
	v_lshlrev_b32_e32 v1, 4, v1
	v_xor_b32_e32 v239, v239, v1
	v_bfe_u32 v1, v0, 4, 4
	v_mul_u32_u24_e32 v1, 0x110, v1
	v_xor_b32_e32 v239, v239, v1
	v_bfe_u32 v1, v0, 8, 1
	v_lshlrev_b32_e32 v1, 12, v1
	v_xor_b32_e32 v239, v239, v1
	v_add_u32_e32 v238, 0x10000, v239
	v_mov_b32_e32 v237, 0x0
	v_bfe_u32 v1, v0, 0, 3
	v_lshlrev_b32_e32 v1, 4, v1
	v_add_u32_e32 v237, v237, v1
	v_bfe_u32 v1, v0, 3, 6
	v_lshlrev_b32_e32 v1, 11, v1
	v_add_u32_e32 v237, v237, v1
	v_add_u32_e32 v236, 0x20000, v237
	v_add_u32_e32 v235, 0x40000, v237
	v_add_u32_e32 v234, 0x60000, v237
	v_mov_b32_e32 v1, v0
	s_load_dword s2, s[0:1], 0xe0
	s_mov_b32 s3, s10
	v_mov_b32_e32 v1, v0
	s_waitcnt lgkmcnt(0)
	s_lshr_b32 s11, s2, 3
	v_cvt_f32_u32_e32 v2, s11
	s_mov_b32 s2, s10
	s_ashr_i32 s3, s2, 3
	v_rcp_iflag_f32_e32 v2, v2
	s_ashr_i32 s4, s2, 31
	s_sub_i32 s2, 0, s11
	s_abs_i32 s3, s3
	v_mul_f32_e32 v1, 0x4f7ffffe, v2
	v_cvt_u32_f32_e32 v1, v1
	s_mov_b32 s45, 0
	v_readfirstlane_b32 s5, v1
	s_mul_i32 s2, s2, s5
	s_mul_hi_u32 s2, s5, s2
	s_add_i32 s2, s5, s2
	s_mul_hi_u32 s5, s3, s2
	s_mul_i32 s5, s5, s11
	s_sub_i32 s3, s3, s5
	s_sub_i32 s5, s3, s11
	s_cmp_ge_u32 s3, s11
	s_cselect_b32 s3, s5, s3
	s_sub_i32 s5, s3, s11
	s_cmp_ge_u32 s3, s11
	s_cselect_b32 s3, s5, s3
	s_xor_b32 s3, s3, s4
	s_sub_i32 s24, s3, s4
	s_mov_b32 s3, s10
	s_cmpk_gt_i32 s24, 0x5f
	s_cbranch_scc1 .LBB0_361
	s_load_dwordx2 s[4:5], s[16:17], 0xd0
	s_mov_b32 s3, s10
	v_mov_b32_e32 v54, 0
	v_mov_b32_e32 v1, v0
	s_waitcnt lgkmcnt(0)
	s_add_u32 s25, s4, 0x17f0000
	s_addc_u32 s26, s5, 0
	s_add_u32 s8, s4, 0x37f0000
	s_addc_u32 s9, s5, 0
	s_add_u32 s27, s4, 0x50000
	s_addc_u32 s28, s5, 0
	s_ashr_i32 s4, s24, 31
	s_lshr_b32 s4, s4, 27
	s_add_i32 s4, s24, s4
	s_ashr_i32 s4, s4, 5
	s_lshl_b32 s5, s24, 1
	s_lshl_b32 s12, s4, 6
	s_sub_i32 s5, s5, s12
	s_lshl_b32 s4, s4, 2
	s_and_b32 s12, s24, 3
	s_or_b32 s29, s4, s12
	s_sub_i32 s4, s11, s24
	s_addk_i32 s4, 0x5f
	s_mul_hi_u32 s2, s4, s2
	s_mul_i32 s12, s2, s11
	s_sub_i32 s4, s4, s12
	s_add_i32 s12, s2, 1
	s_sub_i32 s13, s4, s11
	s_cmp_ge_u32 s4, s11
	s_cselect_b32 s2, s12, s2
	s_cselect_b32 s4, s13, s4
	s_add_i32 s12, s2, 1
	s_cmp_ge_u32 s4, s11
	s_cselect_b32 s2, s12, s2
	s_and_b32 s3, s3, 7
	s_and_b32 s4, s5, -8
	s_lshl_b32 s30, s2, 4
	s_mul_i32 s2, s29, 0xc0
	s_or_b32 s31, s3, s4
	s_ashr_i32 s3, s2, 31
	s_lshl_b64 s[2:3], s[2:3], 11
	v_lshlrev_b32_e32 v2, 8, v1
	v_lshlrev_b32_e32 v1, 4, v1
	s_add_u32 s2, s27, s2
	v_and_b32_e32 v1, 0x70, v1
	s_movk_i32 s33, 0xf800
	v_mov_b32_e32 v175, 0
	s_addc_u32 s3, s28, s3
	v_and_or_b32 v174, v2, s33, v1
	s_lshl_b32 s4, s31, 8
	v_lshl_add_u64 v[2:3], s[2:3], 0, v[174:175]
	s_mov_b32 s12, 0x40000
	s_ashr_i32 s5, s4, 31
	v_add_co_u32_e32 v14, vcc, s12, v2
	s_lshl_b64 s[4:5], s[4:5], 11
	s_nop 0
	v_addc_co_u32_e32 v15, vcc, 0, v3, vcc
	s_mov_b32 s34, 0x20000
	s_add_u32 s4, s25, s4
	v_add_co_u32_e32 v16, vcc, s34, v2
	s_addc_u32 s5, s26, s5
	s_nop 0
	v_addc_co_u32_e32 v17, vcc, 0, v3, vcc
	global_load_dwordx4 v[2:5], v[14:15], off
	global_load_dwordx4 v[6:9], v[16:17], off
	global_load_dwordx4 v[10:13], v174, s[2:3]
	v_lshl_add_u64 v[14:15], s[4:5], 0, v[174:175]
	s_mov_b32 s13, 0x60000
	v_add_co_u32_e32 v30, vcc, s13, v14
	v_mov_b32_e32 v1, v0
	s_nop 0
	v_addc_co_u32_e32 v31, vcc, 0, v15, vcc
	v_add_co_u32_e32 v32, vcc, s12, v14
	s_movk_i32 s36, 0xf0
	s_nop 0
	v_addc_co_u32_e32 v33, vcc, 0, v15, vcc
	v_add_co_u32_e32 v34, vcc, s34, v14
	s_mov_b32 s35, 2
	s_nop 0
	v_addc_co_u32_e32 v35, vcc, 0, v15, vcc
	global_load_dwordx4 v[14:17], v174, s[4:5]
	global_load_dwordx4 v[18:21], v[34:35], off
	global_load_dwordx4 v[22:25], v[32:33], off
	global_load_dwordx4 v[26:29], v[30:31], off
	v_mov_b32_e32 v30, v0
	v_ashrrev_i32_e32 v31, 4, v1
	v_xor_b32_e32 v1, v31, v1
	v_lshlrev_b32_e32 v31, 8, v31
	v_lshlrev_b32_e32 v1, 4, v1
	v_and_or_b32 v1, v1, s36, v31
	s_movk_i32 s37, 0xff80
	s_mov_b32 s38, 0x10000
	s_mov_b32 s39, 0x18000
	s_movk_i32 s40, 0x8a0
	s_movk_i32 s41, 0x1140
	v_mov_b32_e32 v176, 0x18000
	s_mov_b32 s22, 2
	s_mov_b32 s42, s24
	s_mov_b32 s43, s29
	s_mov_b32 s44, s31
	v_mov_b32_e32 v55, v54
	v_mov_b32_e32 v56, v54
	v_mov_b32_e32 v57, v54
	v_mov_b32_e32 v82, v54
	v_mov_b32_e32 v83, v54
	v_mov_b32_e32 v84, v54
	v_mov_b32_e32 v85, v54
	v_mov_b32_e32 v86, v54
	v_mov_b32_e32 v87, v54
	v_mov_b32_e32 v88, v54
	v_mov_b32_e32 v89, v54
	v_mov_b32_e32 v90, v54
	v_mov_b32_e32 v91, v54
	v_mov_b32_e32 v92, v54
	v_mov_b32_e32 v93, v54
	v_mov_b32_e32 v94, v54
	v_mov_b32_e32 v95, v54
	v_mov_b32_e32 v96, v54
	v_mov_b32_e32 v97, v54
	s_waitcnt vmcnt(4)
	ds_write_b128 v1, v[10:13] offset:32768
	ds_write_b128 v1, v[6:9] offset:40960
	ds_write_b128 v1, v[2:5] offset:49152
	s_waitcnt vmcnt(3)
	ds_write_b128 v1, v[14:17]
	s_waitcnt vmcnt(2)
	ds_write_b128 v1, v[18:21] offset:8192
	s_waitcnt vmcnt(1)
	ds_write_b128 v1, v[22:25] offset:16384
	s_waitcnt vmcnt(0)
	ds_write_b128 v1, v[26:29] offset:24576
	v_mov_b32_e32 v98, v54
	v_lshlrev_b32_e32 v2, 4, v30
	v_lshlrev_b32_e32 v1, 8, v30
	v_and_b32_e32 v2, 0x70, v2
	v_and_or_b32 v174, v1, s33, v2
	v_lshl_add_u64 v[2:3], s[2:3], 0, v[174:175]
	v_add_co_u32_e32 v10, vcc, s12, v2
	v_mov_b32_e32 v1, 0x10000
	s_nop 0
	v_addc_co_u32_e32 v11, vcc, 0, v3, vcc
	v_add_co_u32_e32 v12, vcc, s34, v2
	v_mov_b32_e32 v99, v54
	s_nop 0
	v_addc_co_u32_e32 v13, vcc, 0, v3, vcc
	global_load_dwordx4 v[2:5], v[10:11], off offset:128
	global_load_dwordx4 v[6:9], v[12:13], off offset:128
	v_lshl_add_u64 v[10:11], s[4:5], 0, v[174:175]
	v_add_co_u32_e32 v12, vcc, s13, v10
	v_mov_b32_e32 v100, v54
	s_nop 0
	v_addc_co_u32_e32 v13, vcc, 0, v11, vcc
	v_add_co_u32_e32 v22, vcc, s12, v10
	v_mov_b32_e32 v101, v54
	s_nop 0
	v_addc_co_u32_e32 v23, vcc, 0, v11, vcc
	v_add_co_u32_e32 v30, vcc, s34, v10
	global_load_dwordx4 v[14:17], v[12:13], off offset:128
	global_load_dwordx4 v[18:21], v[22:23], off offset:128
	v_addc_co_u32_e32 v31, vcc, 0, v11, vcc
	global_load_dwordx4 v[10:13], v174, s[2:3] offset:128
	global_load_dwordx4 v[22:25], v[30:31], off offset:128
	global_load_dwordx4 v[26:29], v174, s[4:5] offset:128
	v_mov_b32_e32 v102, v54
	v_mov_b32_e32 v103, v54
	v_mov_b32_e32 v104, v54
	v_mov_b32_e32 v105, v54
	v_mov_b32_e32 v106, v54
	v_mov_b32_e32 v107, v54
	v_mov_b32_e32 v108, v54
	v_mov_b32_e32 v109, v54
	v_mov_b32_e32 v110, v54
	v_mov_b32_e32 v111, v54
	v_mov_b32_e32 v112, v54
	v_mov_b32_e32 v113, v54
	v_mov_b32_e32 v114, v54
	v_mov_b32_e32 v115, v54
	v_mov_b32_e32 v116, v54
	v_mov_b32_e32 v117, v54
	v_mov_b32_e32 v118, v54
	v_mov_b32_e32 v119, v54
	v_mov_b32_e32 v120, v54
	v_mov_b32_e32 v121, v54
	v_mov_b32_e32 v122, v54
	v_mov_b32_e32 v123, v54
	v_mov_b32_e32 v124, v54
	v_mov_b32_e32 v125, v54
	v_mov_b32_e32 v78, v54
	v_mov_b32_e32 v79, v54
	v_mov_b32_e32 v80, v54
	v_mov_b32_e32 v81, v54
	v_mov_b32_e32 v74, v54
	v_mov_b32_e32 v75, v54
	v_mov_b32_e32 v76, v54
	v_mov_b32_e32 v77, v54
	v_mov_b32_e32 v70, v54
	v_mov_b32_e32 v71, v54
	v_mov_b32_e32 v72, v54
	v_mov_b32_e32 v73, v54
	v_mov_b32_e32 v66, v54
	v_mov_b32_e32 v67, v54
	v_mov_b32_e32 v68, v54
	v_mov_b32_e32 v69, v54
	v_mov_b32_e32 v62, v54
	v_mov_b32_e32 v63, v54
	v_mov_b32_e32 v64, v54
	v_mov_b32_e32 v65, v54
	v_mov_b32_e32 v58, v54
	v_mov_b32_e32 v59, v54
	v_mov_b32_e32 v60, v54
	v_mov_b32_e32 v61, v54
	v_mov_b32_e32 v50, v54
	v_mov_b32_e32 v51, v54
	v_mov_b32_e32 v52, v54
	v_mov_b32_e32 v53, v54
	v_mov_b32_e32 v46, v54
	v_mov_b32_e32 v47, v54
	v_mov_b32_e32 v48, v54
	v_mov_b32_e32 v49, v54
	v_mov_b32_e32 v42, v54
	v_mov_b32_e32 v43, v54
	v_mov_b32_e32 v44, v54
	v_mov_b32_e32 v45, v54
	v_mov_b32_e32 v38, v54
	v_mov_b32_e32 v39, v54
	v_mov_b32_e32 v40, v54
	v_mov_b32_e32 v41, v54
	v_mov_b32_e32 v34, v54
	v_mov_b32_e32 v35, v54
	v_mov_b32_e32 v36, v54
	v_mov_b32_e32 v37, v54
	v_mov_b32_e32 v30, v54
	v_mov_b32_e32 v31, v54
	v_mov_b32_e32 v32, v54
	v_mov_b32_e32 v33, v54
	s_waitcnt lgkmcnt(0)
	s_barrier
	s_waitcnt vmcnt(0)
	s_branch .LBB0_285

.Lbar_noinv_4:
	s_waitcnt lgkmcnt(0)
	s_barrier
.LBB0_418:
	s_waitcnt vmcnt(0)
	v_mov_b32_e32 v2, v0
	s_mov_b32 s2, s10
	v_ashrrev_i32_e32 v3, 8, v2
	s_movk_i32 s3, 0x200
	v_lshl_add_u32 v1, s2, 1, v3
	v_cmp_gt_i32_e32 vcc, s3, v1
	s_and_saveexec_b64 s[8:9], vcc
	s_cbranch_execz .LBB0_435
	s_load_dword s3, s[0:1], 0xe0
	s_load_dwordx4 s[12:15], s[16:17], 0xc8
	v_lshrrev_b32_e32 v2, 8, v2
	v_mul_i32_i24_e32 v44, 0x10800, v3
	s_mov_b64 s[30:31], 0
	s_waitcnt lgkmcnt(0)
	s_lshl_b32 s11, s3, 1
	s_add_u32 s22, s14, 0x37f0000
	s_addc_u32 s23, s15, 0
	s_add_u32 s24, s14, 0x7cf0000
	s_addc_u32 s25, s15, 0
	s_add_u32 s26, s14, 0xd4b0000
	s_addc_u32 s27, s15, 0
	s_lshl_b32 s2, s2, 1
	v_add_u16_e32 v45, s2, v2
	s_add_u32 s28, s12, 0x4800000
	v_mbcnt_lo_u32_b32 v2, -1, 0
	s_addc_u32 s29, s13, 0
	v_mbcnt_hi_u32_b32 v49, -1, v2
	s_add_u32 s12, s12, 0x4000000
	v_and_b32_e32 v2, 64, v49
	s_addc_u32 s13, s13, 0
	s_mov_b32 s33, 0xbfb8aa3b
	s_mov_b32 s48, 0x42ce8ed0
	s_mov_b32 s49, 0xc2b17218
	s_mov_b32 s50, 0x7f800000
	v_mov_b32_e32 v46, 0x7f800000
	s_mov_b32 s51, 0x3f2aaaab
	v_mov_b32_e32 v47, 0x3ecc95a3
	s_mov_b32 s52, 0x3f317218
	s_mov_b32 s53, 0x33800000
	v_mov_b32_e32 v3, 0
	s_movk_i32 s54, 0x1140
	s_mov_b32 s55, 0x3fb8aa3b
	s_mov_b32 s56, 0xc2ce8ed0
	s_mov_b32 s57, 0x42b17218
	s_movk_i32 s58, 0xfe00
	v_mov_b64_e32 v[4:5], 0x40000
	s_mov_b64 s[34:35], 0x37f0200
	s_mov_b64 s[36:37], 0x37f0300
	v_mov_b32_e32 v48, 0x358637bd
	s_mov_b32 s59, 0x800000
	s_movk_i32 s60, 0x1fff
	s_mov_b32 s61, 0x17f0000
	s_mov_b64 s[38:39], 0x80
	s_mov_b64 s[40:41], 0x200
	s_mov_b64 s[42:43], 0x800
	s_mov_b64 s[44:45], 0x1140
	s_movk_i32 s62, 0xfe
	s_movk_i32 s63, 0x900
	s_movk_i32 s64, 0x110
	s_movk_i32 s65, 0x4000
	s_movk_i32 s66, 0x1ff
	v_add_u32_e32 v50, 64, v2
	v_xor_b32_e32 v51, 32, v49
	v_xor_b32_e32 v52, 16, v49
	v_xor_b32_e32 v53, 8, v49
	v_xor_b32_e32 v54, 4, v49
	v_xor_b32_e32 v55, 2, v49
	v_xor_b32_e32 v56, 1, v49
	v_mov_b32_e32 v57, 7
	s_branch .LBB0_421

.Lbar_noinv_5:
	s_waitcnt lgkmcnt(0)
	s_barrier
.LBB0_493:
	v_mov_b32_e32 v1, v0
	s_mov_b32 s3, s10
	s_load_dword s2, s[0:1], 0xe0
	s_load_dwordx2 s[12:13], s[16:17], 0xd0
	s_waitcnt vmcnt(0)
	v_mov_b32_e32 v2, v0
	s_waitcnt lgkmcnt(0)
	s_add_u32 s14, s12, 0x37f0000
	s_addc_u32 s15, s13, 0
	s_lshr_b32 s11, s2, 3
	v_cvt_f32_u32_e32 v1, s11
	s_sub_i32 s4, 0, s11
	s_mov_b32 s2, s10
	v_rcp_iflag_f32_e32 v1, v1
	s_ashr_i32 s3, s2, 3
	s_abs_i32 s3, s3
	s_ashr_i32 s2, s2, 31
	v_mul_f32_e32 v1, 0x4f7ffffe, v1
	v_cvt_u32_f32_e32 v1, v1
	s_nop 0
	v_readfirstlane_b32 s33, v1
	s_mul_i32 s4, s4, s33
	s_mul_hi_u32 s4, s33, s4
	s_add_i32 s33, s33, s4
	s_mul_hi_u32 s4, s3, s33
	s_mul_i32 s4, s4, s11
	s_sub_i32 s3, s3, s4
	s_sub_i32 s4, s3, s11
	s_cmp_ge_u32 s3, s11
	s_cselect_b32 s3, s4, s3
	s_sub_i32 s4, s3, s11
	s_cmp_ge_u32 s3, s11
	s_cselect_b32 s3, s4, s3
	s_xor_b32 s3, s3, s2
	s_sub_i32 s26, s3, s2
	s_mov_b32 s2, s10
	s_cmp_gt_i32 s26, 23
	s_cbranch_scc1 .LBB0_593
	s_mov_b32 s5, s10
	s_cmpk_gt_i32 s26, 0xffe0
	s_cbranch_scc0 .LBB0_496
	s_bfe_i32 s2, s26, 0x80000
	s_mulk_i32 s2, 0x56
	s_bfe_u32 s3, s2, 0x1000f
	s_bfe_u32 s2, s2, 0x80008
	s_add_i32 s2, s2, s3
	s_sext_i32_i8 s3, s2
	s_mul_i32 s2, s2, 3
	s_sub_i32 s2, s26, s2
	s_lshl_b32 s4, s3, 3
	s_sext_i32_i8 s27, s2
	s_mov_b32 s45, 1
	s_cbranch_execz .LBB0_497
	s_branch .LBB0_498

.Lbar_noinv_6:
	s_waitcnt lgkmcnt(0)
	s_barrier
.LBB0_774:
	s_waitcnt vmcnt(0)
	v_mov_b32_e32 v3, v0
	s_mov_b32 s2, s10
	v_ashrrev_i32_e32 v2, 8, v3
	s_movk_i32 s11, 0x600
	v_lshl_add_u32 v1, s2, 1, v2
	v_cmp_gt_i32_e32 vcc, s11, v1
	s_and_saveexec_b64 s[22:23], vcc
	s_cbranch_execz .LBB0_898
	s_load_dword s3, s[0:1], 0xe0
	s_load_dwordx4 s[12:15], s[16:17], 0xc8
	v_lshrrev_b32_e32 v3, 8, v3
	s_mov_b32 s4, 0x10800
	v_mul_i32_i24_e32 v161, 0x10800, v2
	s_waitcnt lgkmcnt(0)
	s_lshl_b32 s33, s3, 1
	s_add_u32 s24, s14, 0x17f0000
	s_addc_u32 s25, s15, 0
	s_add_u32 s26, s14, 0xc3b0000
	s_addc_u32 s27, s15, 0
	s_add_u32 s28, s14, 0x8130000
	s_addc_u32 s29, s15, 0
	s_add_u32 s30, s14, 0xaa30000
	s_addc_u32 s31, s15, 0
	s_add_u32 s34, s14, 0x40000
	s_addc_u32 s35, s15, 0
	s_add_u32 s36, s14, 0x37f0000
	s_addc_u32 s37, s15, 0
	s_add_u32 s40, s14, 0xd4b0000
	s_addc_u32 s41, s15, 0
	s_add_u32 s12, s12, 0x4a00000
	s_addc_u32 s13, s13, 0
	s_lshl_b32 s2, s2, 1
	v_add_u16_e32 v169, s2, v3
	v_mov_b32_e32 v3, 0x4800
	v_mad_i32_i24 v173, v2, s4, v3
	s_mov_b32 s44, 0x358637bd
	v_mbcnt_lo_u32_b32 v2, -1, 0
	v_mbcnt_hi_u32_b32 v177, -1, v2
	s_mov_b32 s54, 0xfff80000
	v_and_b32_e32 v2, 64, v177
	s_mov_b64 s[38:39], 0xd4b0000
	s_mov_b64 s[42:43], 0
	s_movk_i32 s70, 0x200
	s_movk_i32 s71, 0xff
	s_movk_i32 s72, 0x60
	v_mov_b32_e32 v3, 0
	s_mov_b32 s45, 0x3c2aaaab
	s_mov_b32 s73, 0x800000
	s_mov_b32 s74, 0x8800
	s_movk_i32 s75, 0xab
	s_movk_i32 s76, 0x100
	s_movk_i32 s77, 0x88
	s_movk_i32 s78, 0x3400
	s_mov_b64 s[46:47], 0x18000
	s_mov_b64 s[48:49], 0x30000
	s_mov_b32 s79, 0x8a00
	s_mov_b32 s80, 0xe000
	s_movk_i32 s81, 0x8a0
	s_movk_i32 s82, 0x70
	s_mov_b32 s83, 0xbfb8aa3b
	s_mov_b32 s84, 0x42ce8ed0
	s_mov_b32 s85, 0xc2b17218
	s_mov_b32 s86, 0x7f800000
	s_mov_b32 s87, 0x3f2aaaab
	v_mov_b32_e32 v174, 0x3ecc95a3
	s_mov_b32 s88, 0x3f317218
	s_mov_b32 s89, 0x33800000
	s_mov_b32 s90, 0x3fb8aa3b
	s_mov_b32 s91, 0xc2ce8ed0
	s_mov_b32 s92, 0x42b17218
	s_mov_b32 s93, 0xd4b0000
	s_mov_b64 s[50:51], 0x80000
	s_mov_b64 s[52:53], 0xd4b4000
	s_mov_b32 s94, 0xd4b4000
	s_mov_b32 s55, -1
	s_mov_b64 s[58:59], 0x10000
	s_movk_i32 s95, 0x1140
	v_mov_b32_e32 v175, 0x358637bd
	s_mov_b64 s[60:61], 0x17f0600
	s_mov_b32 s96, 0x17f0000
	s_movk_i32 s97, 0x5ff
	v_mov_b32_e32 v176, 0x2000
	v_xor_b32_e32 v178, 32, v177
	v_add_u32_e32 v179, 64, v2
	v_mov_b32_e32 v180, 4
	v_mov_b32_e32 v181, 0x70
	v_mov_b32_e32 v182, 0x7f800000
	v_mov_b32_e32 v183, 6
	v_mov_b32_e32 v184, 1
	s_branch .LBB0_778

.Lbar_noinv_7:
	s_waitcnt lgkmcnt(0)
	s_barrier
.LBB0_956:
	s_mov_b32 s98, 0
	v_mov_b32_e32 v255, 0x0
	v_bfe_u32 v1, v0, 0, 1
	v_lshlrev_b32_e32 v1, 7, v1
	v_xor_b32_e32 v255, v255, v1
	v_bfe_u32 v1, v0, 1, 3
	v_mul_u32_u24_e32 v1, 0x110, v1
	v_xor_b32_e32 v255, v255, v1
	v_bfe_u32 v1, v0, 4, 2
	v_lshlrev_b32_e32 v1, 4, v1
	v_xor_b32_e32 v255, v255, v1
	v_bfe_u32 v1, v0, 8, 1
	v_lshlrev_b32_e32 v1, 14, v1
	v_xor_b32_e32 v255, v255, v1
	v_add_u32_e32 v254, 0x10000, v255
	v_xor_b32_e32 v253, 0x880, v255
	v_xor_b32_e32 v252, 0x10880, v255
	v_mov_b32_e32 v251, 0x8000
	v_bfe_u32 v1, v0, 0, 1
	v_lshlrev_b32_e32 v1, 7, v1
	v_xor_b32_e32 v251, v251, v1
	v_bfe_u32 v1, v0, 1, 3
	v_mul_u32_u24_e32 v1, 0x110, v1
	v_xor_b32_e32 v251, v251, v1
	v_bfe_u32 v1, v0, 4, 2
	v_lshlrev_b32_e32 v1, 4, v1
	v_xor_b32_e32 v251, v251, v1
	v_bfe_u32 v1, v0, 6, 2
	v_lshlrev_b32_e32 v1, 13, v1
	v_xor_b32_e32 v251, v251, v1
	v_add_u32_e32 v250, 0x10000, v251
	v_xor_b32_e32 v249, 0x880, v251
	v_xor_b32_e32 v248, 0x10880, v251
	v_xor_b32_e32 v247, 0x40, v255
	v_xor_b32_e32 v246, 0x10040, v255
	v_xor_b32_e32 v245, 0x8c0, v255
	v_xor_b32_e32 v244, 0x108c0, v255
	v_xor_b32_e32 v243, 0x40, v251
	v_xor_b32_e32 v242, 0x10040, v251
	v_xor_b32_e32 v241, 0x8c0, v251
	v_xor_b32_e32 v237, 0x108c0, v251
	v_mov_b32_e32 v236, 0x0
	v_bfe_u32 v1, v0, 0, 4
	v_lshlrev_b32_e32 v1, 4, v1
	v_xor_b32_e32 v236, v236, v1
	v_bfe_u32 v1, v0, 4, 4
	v_mul_u32_u24_e32 v1, 0x110, v1
	v_xor_b32_e32 v236, v236, v1
	v_bfe_u32 v1, v0, 8, 1
	v_lshlrev_b32_e32 v1, 12, v1
	v_xor_b32_e32 v236, v236, v1
	v_add_u32_e32 v235, 0x10000, v236
	v_mov_b32_e32 v234, 0x0
	v_bfe_u32 v1, v0, 0, 3
	v_lshlrev_b32_e32 v1, 4, v1
	v_add_u32_e32 v234, v234, v1
	v_bfe_u32 v1, v0, 3, 6
	v_lshlrev_b32_e32 v1, 11, v1
	v_add_u32_e32 v234, v234, v1
	v_add_u32_e32 v233, 0x20000, v234
	v_add_u32_e32 v232, 0x40000, v234
	v_add_u32_e32 v231, 0x60000, v234
	v_mov_b32_e32 v1, v0
	s_load_dword s2, s[0:1], 0xe0
	s_mov_b32 s3, s10
	v_mov_b32_e32 v1, v0
	s_waitcnt lgkmcnt(0)
	s_lshr_b32 s11, s2, 3
	s_waitcnt vmcnt(0)
	v_cvt_f32_u32_e32 v2, s11
	s_mov_b32 s2, s10
	s_ashr_i32 s3, s2, 3
	v_rcp_iflag_f32_e32 v2, v2
	s_ashr_i32 s4, s2, 31
	s_sub_i32 s2, 0, s11
	s_abs_i32 s3, s3
	v_mul_f32_e32 v1, 0x4f7ffffe, v2
	v_cvt_u32_f32_e32 v1, v1
	s_mov_b32 s52, 0
	v_readfirstlane_b32 s5, v1
	s_mul_i32 s2, s2, s5
	s_mul_hi_u32 s2, s5, s2
	s_add_i32 s2, s5, s2
	s_mul_hi_u32 s5, s3, s2
	s_mul_i32 s5, s5, s11
	s_sub_i32 s3, s3, s5
	s_sub_i32 s5, s3, s11
	s_cmp_ge_u32 s3, s11
	s_cselect_b32 s3, s5, s3
	s_sub_i32 s5, s3, s11
	s_cmp_ge_u32 s3, s11
	s_cselect_b32 s3, s5, s3
	s_xor_b32 s3, s3, s4
	s_sub_i32 s30, s3, s4
	s_mov_b32 s3, s10
	s_cmp_gt_i32 s30, 31
	s_cbranch_scc1 .LBB0_1020
	s_load_dwordx4 s[4:7], s[16:17], 0xc8
	s_load_dwordx4 s[12:15], s[16:17], 0x0
	s_mov_b32 s3, s10
	v_mov_b32_e32 v82, 0
	s_waitcnt lgkmcnt(0)
	s_add_u32 s31, s6, 0x17f0000
	s_addc_u32 s33, s7, 0
	s_add_u32 s20, s6, 0x6000
	s_addc_u32 s21, s7, 0
	s_add_u32 s34, s6, 0x570000
	s_addc_u32 s35, s7, 0
	s_ashr_i32 s6, s30, 31
	s_lshr_b32 s6, s6, 27
	s_add_i32 s6, s30, s6
	s_ashr_i32 s6, s6, 5
	s_lshl_b32 s7, s6, 6
	s_lshl_b32 s22, s30, 1
	s_sub_i32 s7, s22, s7
	s_lshl_b32 s6, s6, 2
	s_and_b32 s22, s30, 3
	s_or_b32 s36, s6, s22
	s_sub_i32 s6, s11, s30
	s_add_i32 s6, s6, 31
	s_mul_hi_u32 s2, s6, s2
	s_mul_i32 s22, s2, s11
	s_sub_i32 s6, s6, s22
	s_add_i32 s22, s2, 1
	s_sub_i32 s23, s6, s11
	s_cmp_ge_u32 s6, s11
	s_cselect_b32 s2, s22, s2
	s_cselect_b32 s6, s23, s6
	s_add_i32 s22, s2, 1
	s_cmp_ge_u32 s6, s11
	s_cselect_b32 s2, s22, s2
	s_and_b32 s3, s3, 7
	s_and_b32 s6, s7, -8
	s_lshl_b32 s37, s2, 4
	v_mov_b32_e32 v1, v0
	s_lshl_b32 s2, s36, 8
	s_or_b32 s38, s3, s6
	s_ashr_i32 s3, s2, 31
	s_lshl_b64 s[2:3], s[2:3], 11
	v_lshlrev_b32_e32 v2, 8, v1
	v_lshlrev_b32_e32 v1, 4, v1
	s_add_u32 s2, s34, s2
	v_and_b32_e32 v1, 0x70, v1
	s_movk_i32 s39, 0xf800
	v_mov_b32_e32 v239, 0
	s_addc_u32 s3, s35, s3
	v_and_or_b32 v238, v2, s39, v1
	v_lshl_add_u64 v[10:11], s[2:3], 0, v[238:239]
	s_mov_b32 s40, 0x60000
	v_add_co_u32_e32 v12, vcc, s40, v10
	s_lshl_b32 s6, s38, 8
	s_nop 0
	v_addc_co_u32_e32 v13, vcc, 0, v11, vcc
	s_mov_b32 s22, 0x40000
	s_ashr_i32 s7, s6, 31
	v_add_co_u32_e32 v14, vcc, s22, v10
	s_lshl_b64 s[6:7], s[6:7], 11
	s_nop 0
	v_addc_co_u32_e32 v15, vcc, 0, v11, vcc
	s_mov_b32 s41, 0x20000
	s_add_u32 s6, s31, s6
	v_add_co_u32_e32 v18, vcc, s41, v10
	s_addc_u32 s7, s33, s7
	s_nop 0
	v_addc_co_u32_e32 v19, vcc, 0, v11, vcc
	v_lshl_add_u64 v[30:31], s[6:7], 0, v[238:239]
	v_add_co_u32_e32 v32, vcc, s22, v30
	global_load_dwordx4 v[2:5], v[12:13], off
	global_load_dwordx4 v[6:9], v[14:15], off
	v_addc_co_u32_e32 v33, vcc, 0, v31, vcc
	v_add_co_u32_e32 v34, vcc, s41, v30
	global_load_dwordx4 v[10:13], v[18:19], off
	global_load_dwordx4 v[14:17], v238, s[2:3]
	v_addc_co_u32_e32 v35, vcc, 0, v31, vcc
	global_load_dwordx4 v[18:21], v[32:33], off
	global_load_dwordx4 v[22:25], v[34:35], off
	global_load_dwordx4 v[26:29], v238, s[6:7]
	v_add_co_u32_e32 v30, vcc, s40, v30
	v_mov_b32_e32 v1, v0
	s_nop 0
	v_addc_co_u32_e32 v31, vcc, 0, v31, vcc
	global_load_dwordx4 v[30:33], v[30:31], off
	s_movk_i32 s43, 0xf0
	v_ashrrev_i32_e32 v35, 4, v1
	v_xor_b32_e32 v1, v35, v1
	v_lshlrev_b32_e32 v35, 8, v35
	v_lshlrev_b32_e32 v1, 4, v1
	v_mov_b32_e32 v34, v0
	v_and_or_b32 v1, v1, s43, v35
	s_mov_b32 s42, 2
	s_movk_i32 s44, 0xff80
	s_mov_b32 s45, 0x10000
	s_mov_b32 s46, 0x11000
	s_movk_i32 s47, 0x1800
	s_movk_i32 s48, 0x1fff
	v_mov_b32_e32 v240, 0x8040
	s_mov_b32 s28, 2
	s_mov_b32 s49, s30
	s_mov_b32 s50, s36
	s_mov_b32 s51, s38
	v_mov_b32_e32 v83, v82
	v_mov_b32_e32 v84, v82
	v_mov_b32_e32 v85, v82
	v_mov_b32_e32 v102, v82
	v_mov_b32_e32 v103, v82
	v_mov_b32_e32 v104, v82
	v_mov_b32_e32 v105, v82
	v_mov_b32_e32 v106, v82
	v_mov_b32_e32 v107, v82
	v_mov_b32_e32 v108, v82
	v_mov_b32_e32 v109, v82
	v_mov_b32_e32 v110, v82
	s_waitcnt vmcnt(4)
	ds_write_b128 v1, v[14:17] offset:32768
	ds_write_b128 v1, v[10:13] offset:40960
	ds_write_b128 v1, v[6:9] offset:49152
	ds_write_b128 v1, v[2:5] offset:57344
	s_waitcnt vmcnt(1)
	ds_write_b128 v1, v[26:29]
	ds_write_b128 v1, v[22:25] offset:8192
	ds_write_b128 v1, v[18:21] offset:16384
	s_waitcnt vmcnt(0)
	ds_write_b128 v1, v[30:33] offset:24576
	v_mov_b32_e32 v111, v82
	v_lshlrev_b32_e32 v2, 4, v34
	v_lshlrev_b32_e32 v1, 8, v34
	v_and_b32_e32 v2, 0x70, v2
	v_and_or_b32 v238, v1, s39, v2
	v_lshl_add_u64 v[10:11], s[2:3], 0, v[238:239]
	v_add_co_u32_e32 v12, vcc, s40, v10
	v_lshl_add_u64 v[16:17], s[6:7], 0, v[238:239]
	s_nop 0
	v_addc_co_u32_e32 v13, vcc, 0, v11, vcc
	v_add_co_u32_e32 v14, vcc, s22, v10
	v_mov_b32_e32 v1, 0x10000
	s_nop 0
	v_addc_co_u32_e32 v15, vcc, 0, v11, vcc
	global_load_dwordx4 v[2:5], v[12:13], off offset:128
	global_load_dwordx4 v[6:9], v[14:15], off offset:128
	v_add_co_u32_e32 v14, vcc, s41, v10
	v_mov_b32_e32 v112, v82
	s_nop 0
	v_addc_co_u32_e32 v15, vcc, 0, v11, vcc
	v_add_co_u32_e32 v22, vcc, s40, v16
	v_mov_b32_e32 v113, v82
	s_nop 0
	v_addc_co_u32_e32 v23, vcc, 0, v17, vcc
	v_add_co_u32_e32 v34, vcc, s22, v16
	global_load_dwordx4 v[10:13], v[14:15], off offset:128
	global_load_dwordx4 v[18:21], v[22:23], off offset:128
	v_addc_co_u32_e32 v35, vcc, 0, v17, vcc
	v_add_co_u32_e32 v36, vcc, s41, v16
	v_mov_b32_e32 v114, v82
	s_nop 0
	v_addc_co_u32_e32 v37, vcc, 0, v17, vcc
	global_load_dwordx4 v[22:25], v[34:35], off offset:128
	global_load_dwordx4 v[26:29], v[36:37], off offset:128
	global_load_dwordx4 v[14:17], v238, s[2:3] offset:128
	global_load_dwordx4 v[30:33], v238, s[6:7] offset:128
	v_mov_b32_e32 v115, v82
	v_mov_b32_e32 v116, v82
	v_mov_b32_e32 v117, v82
	v_mov_b32_e32 v118, v82
	v_mov_b32_e32 v119, v82
	v_mov_b32_e32 v120, v82
	v_mov_b32_e32 v121, v82
	v_mov_b32_e32 v122, v82
	v_mov_b32_e32 v123, v82
	v_mov_b32_e32 v124, v82
	v_mov_b32_e32 v125, v82
	v_mov_b32_e32 v126, v82
	v_mov_b32_e32 v127, v82
	v_mov_b32_e32 v128, v82
	v_mov_b32_e32 v129, v82
	v_mov_b32_e32 v130, v82
	v_mov_b32_e32 v131, v82
	v_mov_b32_e32 v132, v82
	v_mov_b32_e32 v133, v82
	v_mov_b32_e32 v134, v82
	v_mov_b32_e32 v135, v82
	v_mov_b32_e32 v136, v82
	v_mov_b32_e32 v137, v82
	v_mov_b32_e32 v138, v82
	v_mov_b32_e32 v139, v82
	v_mov_b32_e32 v140, v82
	v_mov_b32_e32 v141, v82
	v_mov_b32_e32 v142, v82
	v_mov_b32_e32 v143, v82
	v_mov_b32_e32 v144, v82
	v_mov_b32_e32 v145, v82
	v_mov_b32_e32 v146, v82
	v_mov_b32_e32 v147, v82
	v_mov_b32_e32 v148, v82
	v_mov_b32_e32 v149, v82
	v_mov_b32_e32 v150, v82
	v_mov_b32_e32 v151, v82
	v_mov_b32_e32 v152, v82
	v_mov_b32_e32 v153, v82
	v_mov_b32_e32 v154, v82
	v_mov_b32_e32 v155, v82
	v_mov_b32_e32 v156, v82
	v_mov_b32_e32 v157, v82
	v_mov_b32_e32 v158, v82
	v_mov_b32_e32 v159, v82
	v_mov_b32_e32 v160, v82
	v_mov_b32_e32 v161, v82
	v_mov_b32_e32 v98, v82
	v_mov_b32_e32 v99, v82
	v_mov_b32_e32 v100, v82
	v_mov_b32_e32 v101, v82
	v_mov_b32_e32 v94, v82
	v_mov_b32_e32 v95, v82
	v_mov_b32_e32 v96, v82
	v_mov_b32_e32 v97, v82
	v_mov_b32_e32 v90, v82
	v_mov_b32_e32 v91, v82
	v_mov_b32_e32 v92, v82
	v_mov_b32_e32 v93, v82
	v_mov_b32_e32 v86, v82
	v_mov_b32_e32 v87, v82
	v_mov_b32_e32 v88, v82
	v_mov_b32_e32 v89, v82
	v_mov_b32_e32 v78, v82
	v_mov_b32_e32 v79, v82
	v_mov_b32_e32 v80, v82
	v_mov_b32_e32 v81, v82
	v_mov_b32_e32 v74, v82
	v_mov_b32_e32 v75, v82
	v_mov_b32_e32 v76, v82
	v_mov_b32_e32 v77, v82
	v_mov_b32_e32 v70, v82
	v_mov_b32_e32 v71, v82
	v_mov_b32_e32 v72, v82
	v_mov_b32_e32 v73, v82
	v_mov_b32_e32 v66, v82
	v_mov_b32_e32 v67, v82
	v_mov_b32_e32 v68, v82
	v_mov_b32_e32 v69, v82
	v_mov_b32_e32 v62, v82
	v_mov_b32_e32 v63, v82
	v_mov_b32_e32 v64, v82
	v_mov_b32_e32 v65, v82
	v_mov_b32_e32 v58, v82
	v_mov_b32_e32 v59, v82
	v_mov_b32_e32 v60, v82
	v_mov_b32_e32 v61, v82
	v_mov_b32_e32 v54, v82
	v_mov_b32_e32 v55, v82
	v_mov_b32_e32 v56, v82
	v_mov_b32_e32 v57, v82
	v_mov_b32_e32 v50, v82
	v_mov_b32_e32 v51, v82
	v_mov_b32_e32 v52, v82
	v_mov_b32_e32 v53, v82
	v_mov_b32_e32 v46, v82
	v_mov_b32_e32 v47, v82
	v_mov_b32_e32 v48, v82
	v_mov_b32_e32 v49, v82
	v_mov_b32_e32 v42, v82
	v_mov_b32_e32 v43, v82
	v_mov_b32_e32 v44, v82
	v_mov_b32_e32 v45, v82
	v_mov_b32_e32 v38, v82
	v_mov_b32_e32 v39, v82
	v_mov_b32_e32 v40, v82
	v_mov_b32_e32 v41, v82
	v_mov_b32_e32 v34, v82
	v_mov_b32_e32 v35, v82
	v_mov_b32_e32 v36, v82
	v_mov_b32_e32 v37, v82
	s_waitcnt lgkmcnt(0)
	s_barrier
	s_waitcnt vmcnt(0)
	s_branch .LBB0_960

.Lbar_noinv_8:
	s_waitcnt lgkmcnt(0)
	s_barrier
.LBB0_1077:
	v_mov_b32_e32 v1, v0
	s_mov_b32 s2, s10
	s_waitcnt vmcnt(0)
	v_ashrrev_i32_e32 v2, 8, v1
	s_movk_i32 s3, 0x800
	v_lshl_add_u32 v1, s2, 1, v2
	v_cmp_gt_i32_e32 vcc, s3, v1
	s_and_saveexec_b64 s[8:9], vcc
	s_cbranch_execz .LBB0_1080
	s_load_dword s3, s[0:1], 0xe0
	s_load_dwordx4 s[4:7], s[16:17], 0xc8
	v_lshlrev_b32_e32 v2, 3, v2
	v_lshl_add_u32 v13, s2, 4, v2
	v_mbcnt_lo_u32_b32 v2, -1, 0
	s_waitcnt lgkmcnt(0)
	s_lshl_b32 s11, s3, 1
	s_add_u32 s20, s6, 0x4000
	s_addc_u32 s21, s7, 0
	v_mbcnt_hi_u32_b32 v20, -1, v2
	s_add_u32 s6, s6, 0x17f0000
	v_and_b32_e32 v2, 64, v20
	s_mov_b64 s[14:15], 0x4000
	s_addc_u32 s7, s7, 0
	s_lshl_b32 s27, s3, 4
	s_mov_b64 s[22:23], 0
	v_mov_b32_e32 v11, 0
	s_movk_i32 s30, 0x1800
	s_movk_i32 s31, 0x1fff
	s_movk_i32 s33, 0x1000
	v_add_u32_e32 v21, 64, v2
	v_xor_b32_e32 v22, 32, v20
	v_xor_b32_e32 v23, 16, v20
	v_xor_b32_e32 v24, 8, v20
	v_xor_b32_e32 v25, 4, v20
	v_xor_b32_e32 v26, 2, v20
	v_xor_b32_e32 v27, 1, v20
	s_mov_b64 s[24:25], 0x3000
	s_mov_b32 s26, 0x3a800000
	v_mov_b32_e32 v12, 0x358637bd
	s_mov_b32 s34, 0x800000
	s_movk_i32 s35, 0x7ff

.Lbar_noinv_9:
	s_waitcnt lgkmcnt(0)
	s_barrier
.LBB0_1138:
	s_mov_b32 s98, 0
	v_mov_b32_e32 v255, 0x0
	v_bfe_u32 v1, v0, 0, 1
	v_lshlrev_b32_e32 v1, 7, v1
	v_xor_b32_e32 v255, v255, v1
	v_bfe_u32 v1, v0, 1, 3
	v_mul_u32_u24_e32 v1, 0x110, v1
	v_xor_b32_e32 v255, v255, v1
	v_bfe_u32 v1, v0, 4, 2
	v_lshlrev_b32_e32 v1, 4, v1
	v_xor_b32_e32 v255, v255, v1
	v_bfe_u32 v1, v0, 8, 1
	v_lshlrev_b32_e32 v1, 14, v1
	v_xor_b32_e32 v255, v255, v1
	v_add_u32_e32 v254, 0x10000, v255
	v_xor_b32_e32 v253, 0x880, v255
	v_xor_b32_e32 v252, 0x10880, v255
	v_mov_b32_e32 v251, 0x8000
	v_bfe_u32 v1, v0, 0, 1
	v_lshlrev_b32_e32 v1, 7, v1
	v_xor_b32_e32 v251, v251, v1
	v_bfe_u32 v1, v0, 1, 3
	v_mul_u32_u24_e32 v1, 0x110, v1
	v_xor_b32_e32 v251, v251, v1
	v_bfe_u32 v1, v0, 4, 2
	v_lshlrev_b32_e32 v1, 4, v1
	v_xor_b32_e32 v251, v251, v1
	v_bfe_u32 v1, v0, 6, 2
	v_lshlrev_b32_e32 v1, 13, v1
	v_xor_b32_e32 v251, v251, v1
	v_add_u32_e32 v250, 0x10000, v251
	v_xor_b32_e32 v249, 0x880, v251
	v_xor_b32_e32 v248, 0x10880, v251
	v_xor_b32_e32 v247, 0x40, v255
	v_xor_b32_e32 v246, 0x10040, v255
	v_xor_b32_e32 v245, 0x8c0, v255
	v_xor_b32_e32 v244, 0x108c0, v255
	v_xor_b32_e32 v243, 0x40, v251
	v_xor_b32_e32 v242, 0x10040, v251
	v_xor_b32_e32 v241, 0x8c0, v251
	v_xor_b32_e32 v237, 0x108c0, v251
	v_mov_b32_e32 v236, 0x0
	v_bfe_u32 v1, v0, 0, 4
	v_lshlrev_b32_e32 v1, 4, v1
	v_xor_b32_e32 v236, v236, v1
	v_bfe_u32 v1, v0, 4, 4
	v_mul_u32_u24_e32 v1, 0x110, v1
	v_xor_b32_e32 v236, v236, v1
	v_bfe_u32 v1, v0, 8, 1
	v_lshlrev_b32_e32 v1, 12, v1
	v_xor_b32_e32 v236, v236, v1
	v_add_u32_e32 v235, 0x10000, v236
	v_mov_b32_e32 v234, 0x0
	v_bfe_u32 v1, v0, 0, 3
	v_lshlrev_b32_e32 v1, 4, v1
	v_add_u32_e32 v234, v234, v1
	v_bfe_u32 v1, v0, 3, 6
	v_lshlrev_b32_e32 v1, 11, v1
	v_add_u32_e32 v234, v234, v1
	v_add_u32_e32 v233, 0x20000, v234
	v_add_u32_e32 v232, 0x40000, v234
	v_add_u32_e32 v231, 0x60000, v234
	v_mov_b32_e32 v1, v0
	s_mov_b32 s2, s10
	s_load_dword s8, s[0:1], 0xe0
	s_load_dwordx2 s[2:3], s[16:17], 0xd0
	s_waitcnt vmcnt(0)
	v_mov_b32_e32 v2, v0
	s_mov_b32 s27, 0
	s_waitcnt lgkmcnt(0)
	s_add_u32 s11, s2, 0x17f0000
	s_addc_u32 s24, s3, 0
	s_add_u32 s6, s2, 0x37f0000
	s_addc_u32 s7, s3, 0
	s_add_u32 s25, s2, 0x770000
	s_addc_u32 s26, s3, 0
	s_lshr_b32 s28, s8, 3
	v_cvt_f32_u32_e32 v1, s28
	s_sub_i32 s8, 0, s28
	s_mov_b32 s2, s10
	v_rcp_iflag_f32_e32 v1, v1
	s_ashr_i32 s3, s2, 3
	s_abs_i32 s3, s3
	s_ashr_i32 s2, s2, 31
	v_mul_f32_e32 v1, 0x4f7ffffe, v1
	v_cvt_u32_f32_e32 v1, v1
	s_nop 0
	v_readfirstlane_b32 s30, v1
	s_mul_i32 s8, s8, s30
	s_mul_hi_u32 s8, s30, s8
	s_add_i32 s30, s30, s8
	s_mul_hi_u32 s8, s3, s30
	s_mul_i32 s8, s8, s28
	s_sub_i32 s3, s3, s8
	s_sub_i32 s8, s3, s28
	s_cmp_ge_u32 s3, s28
	s_cselect_b32 s3, s8, s3
	s_sub_i32 s8, s3, s28
	s_cmp_ge_u32 s3, s28
	s_cselect_b32 s3, s8, s3
	s_xor_b32 s3, s3, s2
	s_sub_i32 s31, s3, s2
	s_mul_hi_u32 s3, s30, 0xb0
	s_mul_i32 s3, s3, s28
	s_sub_i32 s3, 0xb0, s3
	s_sub_i32 s8, s3, s28
	s_cmp_ge_u32 s3, s28
	s_cselect_b32 s3, s8, s3
	s_sub_i32 s8, s3, s28
	s_cmp_ge_u32 s3, s28
	s_cselect_b32 s29, s8, s3
	s_sub_i32 s33, 0xb0, s29
	s_mov_b32 s2, s10
	s_cmp_ge_i32 s31, s33
	s_cbranch_scc1 .LBB0_1187
	s_mov_b32 s9, s10
	s_cmpk_gt_i32 s31, 0x9f
	s_cbranch_scc0 .LBB0_1141
	s_lshl_b32 s2, s31, 2
	s_add_i32 s2, s2, 0x7ffffd80
	s_and_b32 s8, s2, 0x7ffffff8
	s_and_b32 s2, s31, 1
	s_or_b32 s34, s2, 20
	s_cbranch_execz .LBB0_1142
	s_branch .LBB0_1143

.Lbar_noinv_10:
	s_waitcnt lgkmcnt(0)
	s_barrier
.LBB0_1298:
	s_mov_b32 s98, 0
	v_mov_b32_e32 v255, 0x0
	v_bfe_u32 v1, v0, 0, 1
	v_lshlrev_b32_e32 v1, 7, v1
	v_xor_b32_e32 v255, v255, v1
	v_bfe_u32 v1, v0, 1, 3
	v_mul_u32_u24_e32 v1, 0x110, v1
	v_xor_b32_e32 v255, v255, v1
	v_bfe_u32 v1, v0, 4, 2
	v_lshlrev_b32_e32 v1, 4, v1
	v_xor_b32_e32 v255, v255, v1
	v_bfe_u32 v1, v0, 8, 1
	v_lshlrev_b32_e32 v1, 14, v1
	v_xor_b32_e32 v255, v255, v1
	v_add_u32_e32 v254, 0x10000, v255
	v_xor_b32_e32 v253, 0x880, v255
	v_xor_b32_e32 v252, 0x10880, v255
	v_mov_b32_e32 v251, 0x8000
	v_bfe_u32 v1, v0, 0, 1
	v_lshlrev_b32_e32 v1, 7, v1
	v_xor_b32_e32 v251, v251, v1
	v_bfe_u32 v1, v0, 1, 3
	v_mul_u32_u24_e32 v1, 0x110, v1
	v_xor_b32_e32 v251, v251, v1
	v_bfe_u32 v1, v0, 4, 2
	v_lshlrev_b32_e32 v1, 4, v1
	v_xor_b32_e32 v251, v251, v1
	v_bfe_u32 v1, v0, 6, 2
	v_lshlrev_b32_e32 v1, 13, v1
	v_xor_b32_e32 v251, v251, v1
	v_add_u32_e32 v250, 0x10000, v251
	v_xor_b32_e32 v249, 0x880, v251
	v_xor_b32_e32 v248, 0x10880, v251
	v_xor_b32_e32 v247, 0x40, v255
	v_xor_b32_e32 v246, 0x10040, v255
	v_xor_b32_e32 v245, 0x8c0, v255
	v_xor_b32_e32 v244, 0x108c0, v255
	v_xor_b32_e32 v243, 0x40, v251
	v_xor_b32_e32 v242, 0x10040, v251
	v_xor_b32_e32 v241, 0x8c0, v251
	v_xor_b32_e32 v237, 0x108c0, v251
	v_mov_b32_e32 v236, 0x0
	v_bfe_u32 v1, v0, 0, 4
	v_lshlrev_b32_e32 v1, 4, v1
	v_xor_b32_e32 v236, v236, v1
	v_bfe_u32 v1, v0, 4, 4
	v_mul_u32_u24_e32 v1, 0x110, v1
	v_xor_b32_e32 v236, v236, v1
	v_bfe_u32 v1, v0, 8, 1
	v_lshlrev_b32_e32 v1, 12, v1
	v_xor_b32_e32 v236, v236, v1
	v_add_u32_e32 v235, 0x10000, v236
	v_mov_b32_e32 v234, 0x0
	v_bfe_u32 v1, v0, 0, 3
	v_lshlrev_b32_e32 v1, 4, v1
	v_add_u32_e32 v234, v234, v1
	v_bfe_u32 v1, v0, 3, 6
	v_mul_u32_u24_e32 v1, 0x1600, v1
	v_add_u32_e32 v234, v234, v1
	v_add_u32_e32 v233, 0x58000, v234
	v_add_u32_e32 v232, 0xb0000, v234
	v_add_u32_e32 v231, 0x108000, v234
	v_mov_b32_e32 v1, v0
	s_load_dword s2, s[0:1], 0xe0
	s_mov_b32 s3, s10
	v_mov_b32_e32 v1, v0
	s_waitcnt lgkmcnt(0)
	s_lshr_b32 s11, s2, 3
	s_waitcnt vmcnt(0)
	v_cvt_f32_u32_e32 v2, s11
	s_mov_b32 s2, s10
	s_ashr_i32 s3, s2, 3
	v_rcp_iflag_f32_e32 v2, v2
	s_ashr_i32 s4, s2, 31
	s_sub_i32 s2, 0, s11
	s_abs_i32 s3, s3
	v_mul_f32_e32 v1, 0x4f7ffffe, v2
	v_cvt_u32_f32_e32 v1, v1
	s_mov_b32 s50, 0
	v_readfirstlane_b32 s5, v1
	s_mul_i32 s2, s2, s5
	s_mul_hi_u32 s2, s5, s2
	s_add_i32 s2, s5, s2
	s_mul_hi_u32 s5, s3, s2
	s_mul_i32 s5, s5, s11
	s_sub_i32 s3, s3, s5
	s_sub_i32 s5, s3, s11
	s_cmp_ge_u32 s3, s11
	s_cselect_b32 s3, s5, s3
	s_sub_i32 s5, s3, s11
	s_cmp_ge_u32 s3, s11
	s_cselect_b32 s3, s5, s3
	s_xor_b32 s3, s3, s4
	s_sub_i32 s28, s3, s4
	s_mov_b32 s3, s10
	s_cmp_gt_i32 s28, 31
	s_cbranch_scc1 .LBB0_1362
	s_load_dwordx4 s[4:7], s[16:17], 0xc8
	s_mov_b32 s3, s10
	v_mov_b32_e32 v82, 0
	v_mov_b32_e32 v1, v0
	s_waitcnt lgkmcnt(0)
	s_add_u32 s12, s4, 0x2000000
	s_addc_u32 s13, s5, 0
	s_add_u32 s14, s6, 0x9000
	s_addc_u32 s15, s7, 0
	s_add_u32 s29, s6, 0x37f0000
	s_addc_u32 s30, s7, 0
	s_add_u32 s31, s6, 0x1270000
	s_addc_u32 s33, s7, 0
	s_ashr_i32 s6, s28, 31
	s_lshr_b32 s6, s6, 27
	s_add_i32 s6, s28, s6
	s_ashr_i32 s6, s6, 5
	s_lshl_b32 s7, s28, 1
	s_lshl_b32 s20, s6, 6
	s_sub_i32 s7, s7, s20
	s_lshl_b32 s6, s6, 2
	s_and_b32 s20, s28, 3
	s_or_b32 s34, s6, s20
	s_sub_i32 s6, s11, s28
	s_add_i32 s6, s6, 31
	s_mul_hi_u32 s2, s6, s2
	s_mul_i32 s20, s2, s11
	s_sub_i32 s6, s6, s20
	s_add_i32 s20, s2, 1
	s_sub_i32 s21, s6, s11
	s_cmp_ge_u32 s6, s11
	s_cselect_b32 s2, s20, s2
	s_cselect_b32 s6, s21, s6
	s_add_i32 s20, s2, 1
	s_cmp_ge_u32 s6, s11
	s_cselect_b32 s41, s20, s2
	s_and_b32 s2, s3, 7
	s_and_b32 s3, s7, -8
	s_movk_i32 s35, 0xb00
	v_lshrrev_b32_e32 v2, 3, v1
	s_or_b32 s36, s2, s3
	s_lshl_b32 s2, s34, 8
	s_mul_i32 s3, s34, 0x160000
	v_mul_lo_u32 v2, v2, s35
	v_lshlrev_b32_e32 v1, 3, v1
	s_mul_hi_i32 s6, s2, 0x1600
	s_add_u32 s2, s31, s3
	v_and_or_b32 v1, v1, 56, v2
	v_mov_b32_e32 v239, 0
	s_addc_u32 s3, s33, s6
	v_lshlrev_b32_e32 v238, 1, v1
	v_lshl_add_u64 v[2:3], s[2:3], 0, v[238:239]
	s_mov_b32 s37, 0x108000
	v_add_co_u32_e32 v34, vcc, s37, v2
	s_mov_b32 s20, 0xb0000
	s_nop 0
	v_addc_co_u32_e32 v35, vcc, 0, v3, vcc
	v_add_co_u32_e32 v36, vcc, s20, v2
	s_lshl_b32 s6, s36, 8
	s_mul_i32 s7, s36, 0x160000
	v_addc_co_u32_e32 v37, vcc, 0, v3, vcc
	s_mov_b32 s38, 0x58000
	s_mul_hi_i32 s21, s6, 0x1600
	s_add_u32 s6, s29, s7
	v_add_co_u32_e32 v2, vcc, s38, v2
	s_addc_u32 s7, s30, s21
	s_nop 0
	v_addc_co_u32_e32 v3, vcc, 0, v3, vcc
	v_lshl_add_u64 v[22:23], s[6:7], 0, v[238:239]
	v_add_co_u32_e32 v24, vcc, s20, v22
	global_load_dwordx4 v[2:5], v[2:3], off
	s_nop 0
	v_addc_co_u32_e32 v25, vcc, 0, v23, vcc
	v_add_co_u32_e32 v26, vcc, s38, v22
	v_mov_b32_e32 v1, v0
	s_nop 0
	v_addc_co_u32_e32 v27, vcc, 0, v23, vcc
	v_add_co_u32_e32 v38, vcc, s37, v22
	global_load_dwordx4 v[6:9], v[24:25], off
	global_load_dwordx4 v[10:13], v[26:27], off
	global_load_dwordx4 v[14:17], v238, s[2:3]
	global_load_dwordx4 v[18:21], v238, s[6:7]
	v_addc_co_u32_e32 v39, vcc, 0, v23, vcc
	global_load_dwordx4 v[22:25], v[38:39], off
	global_load_dwordx4 v[26:29], v[36:37], off
	global_load_dwordx4 v[30:33], v[34:35], off
	s_movk_i32 s40, 0xf0
	v_ashrrev_i32_e32 v34, 4, v1
	v_xor_b32_e32 v1, v34, v1
	v_lshlrev_b32_e32 v34, 8, v34
	v_lshlrev_b32_e32 v1, 4, v1
	v_and_or_b32 v1, v1, s40, v34
	s_mov_b32 s39, 2
	s_mul_i32 s41, s41, 44
	s_movk_i32 s42, 0xff80
	s_mov_b32 s43, 0x10000
	s_mov_b32 s44, 0x11000
	s_movk_i32 s45, 0x1800
	s_movk_i32 s46, 0x1fff
	v_mov_b32_e32 v240, 0x8040
	s_mov_b32 s26, 2
	s_mov_b32 s47, s28
	s_mov_b32 s48, s34
	s_mov_b32 s49, s36
	v_mov_b32_e32 v83, v82
	v_mov_b32_e32 v84, v82
	v_mov_b32_e32 v85, v82
	v_mov_b32_e32 v102, v82
	v_mov_b32_e32 v103, v82
	v_mov_b32_e32 v104, v82
	v_mov_b32_e32 v105, v82
	v_mov_b32_e32 v106, v82
	v_mov_b32_e32 v107, v82
	v_mov_b32_e32 v108, v82
	v_mov_b32_e32 v109, v82
	v_mov_b32_e32 v110, v82
	v_mov_b32_e32 v111, v82
	v_mov_b32_e32 v112, v82
	v_mov_b32_e32 v113, v82
	s_waitcnt vmcnt(4)
	ds_write_b128 v1, v[14:17] offset:32768
	s_waitcnt vmcnt(3)
	ds_write_b128 v1, v[18:21]
	ds_write_b128 v1, v[2:5] offset:40960
	ds_write_b128 v1, v[10:13] offset:8192
	ds_write_b128 v1, v[6:9] offset:16384
	s_waitcnt vmcnt(2)
	ds_write_b128 v1, v[22:25] offset:24576
	s_waitcnt vmcnt(1)
	ds_write_b128 v1, v[26:29] offset:49152
	s_waitcnt vmcnt(0)
	ds_write_b128 v1, v[30:33] offset:57344
	v_mov_b32_e32 v1, v0
	v_mov_b32_e32 v114, v82
	v_lshrrev_b32_e32 v2, 3, v1
	v_mul_lo_u32 v2, v2, s35
	v_lshlrev_b32_e32 v1, 3, v1
	v_and_or_b32 v1, v1, 56, v2
	v_lshlrev_b32_e32 v238, 1, v1
	v_lshl_add_u64 v[10:11], s[2:3], 0, v[238:239]
	v_add_co_u32_e32 v12, vcc, s37, v10
	v_lshl_add_u64 v[16:17], s[6:7], 0, v[238:239]
	s_nop 0
	v_addc_co_u32_e32 v13, vcc, 0, v11, vcc
	v_add_co_u32_e32 v14, vcc, s20, v10
	v_mov_b32_e32 v1, 0x10000
	s_nop 0
	v_addc_co_u32_e32 v15, vcc, 0, v11, vcc
	global_load_dwordx4 v[2:5], v[12:13], off offset:128
	global_load_dwordx4 v[6:9], v[14:15], off offset:128
	v_add_co_u32_e32 v14, vcc, s38, v10
	v_mov_b32_e32 v115, v82
	s_nop 0
	v_addc_co_u32_e32 v15, vcc, 0, v11, vcc
	v_add_co_u32_e32 v22, vcc, s37, v16
	v_mov_b32_e32 v116, v82
	s_nop 0
	v_addc_co_u32_e32 v23, vcc, 0, v17, vcc
	v_add_co_u32_e32 v34, vcc, s20, v16
	global_load_dwordx4 v[10:13], v[14:15], off offset:128
	global_load_dwordx4 v[18:21], v[22:23], off offset:128
	v_addc_co_u32_e32 v35, vcc, 0, v17, vcc
	v_add_co_u32_e32 v36, vcc, s38, v16
	v_mov_b32_e32 v117, v82
	s_nop 0
	v_addc_co_u32_e32 v37, vcc, 0, v17, vcc
	global_load_dwordx4 v[22:25], v[34:35], off offset:128
	global_load_dwordx4 v[26:29], v[36:37], off offset:128
	global_load_dwordx4 v[14:17], v238, s[2:3] offset:128
	global_load_dwordx4 v[30:33], v238, s[6:7] offset:128
	v_mov_b32_e32 v118, v82
	v_mov_b32_e32 v119, v82
	v_mov_b32_e32 v120, v82
	v_mov_b32_e32 v121, v82
	v_mov_b32_e32 v122, v82
	v_mov_b32_e32 v123, v82
	v_mov_b32_e32 v124, v82
	v_mov_b32_e32 v125, v82
	v_mov_b32_e32 v126, v82
	v_mov_b32_e32 v127, v82
	v_mov_b32_e32 v128, v82
	v_mov_b32_e32 v129, v82
	v_mov_b32_e32 v130, v82
	v_mov_b32_e32 v131, v82
	v_mov_b32_e32 v132, v82
	v_mov_b32_e32 v133, v82
	v_mov_b32_e32 v134, v82
	v_mov_b32_e32 v135, v82
	v_mov_b32_e32 v136, v82
	v_mov_b32_e32 v137, v82
	v_mov_b32_e32 v138, v82
	v_mov_b32_e32 v139, v82
	v_mov_b32_e32 v140, v82
	v_mov_b32_e32 v141, v82
	v_mov_b32_e32 v142, v82
	v_mov_b32_e32 v143, v82
	v_mov_b32_e32 v144, v82
	v_mov_b32_e32 v145, v82
	v_mov_b32_e32 v146, v82
	v_mov_b32_e32 v147, v82
	v_mov_b32_e32 v148, v82
	v_mov_b32_e32 v149, v82
	v_mov_b32_e32 v150, v82
	v_mov_b32_e32 v151, v82
	v_mov_b32_e32 v152, v82
	v_mov_b32_e32 v153, v82
	v_mov_b32_e32 v154, v82
	v_mov_b32_e32 v155, v82
	v_mov_b32_e32 v156, v82
	v_mov_b32_e32 v157, v82
	v_mov_b32_e32 v158, v82
	v_mov_b32_e32 v159, v82
	v_mov_b32_e32 v160, v82
	v_mov_b32_e32 v161, v82
	v_mov_b32_e32 v98, v82
	v_mov_b32_e32 v99, v82
	v_mov_b32_e32 v100, v82
	v_mov_b32_e32 v101, v82
	v_mov_b32_e32 v94, v82
	v_mov_b32_e32 v95, v82
	v_mov_b32_e32 v96, v82
	v_mov_b32_e32 v97, v82
	v_mov_b32_e32 v90, v82
	v_mov_b32_e32 v91, v82
	v_mov_b32_e32 v92, v82
	v_mov_b32_e32 v93, v82
	v_mov_b32_e32 v86, v82
	v_mov_b32_e32 v87, v82
	v_mov_b32_e32 v88, v82
	v_mov_b32_e32 v89, v82
	v_mov_b32_e32 v78, v82
	v_mov_b32_e32 v79, v82
	v_mov_b32_e32 v80, v82
	v_mov_b32_e32 v81, v82
	v_mov_b32_e32 v74, v82
	v_mov_b32_e32 v75, v82
	v_mov_b32_e32 v76, v82
	v_mov_b32_e32 v77, v82
	v_mov_b32_e32 v70, v82
	v_mov_b32_e32 v71, v82
	v_mov_b32_e32 v72, v82
	v_mov_b32_e32 v73, v82
	v_mov_b32_e32 v66, v82
	v_mov_b32_e32 v67, v82
	v_mov_b32_e32 v68, v82
	v_mov_b32_e32 v69, v82
	v_mov_b32_e32 v62, v82
	v_mov_b32_e32 v63, v82
	v_mov_b32_e32 v64, v82
	v_mov_b32_e32 v65, v82
	v_mov_b32_e32 v58, v82
	v_mov_b32_e32 v59, v82
	v_mov_b32_e32 v60, v82
	v_mov_b32_e32 v61, v82
	v_mov_b32_e32 v54, v82
	v_mov_b32_e32 v55, v82
	v_mov_b32_e32 v56, v82
	v_mov_b32_e32 v57, v82
	v_mov_b32_e32 v50, v82
	v_mov_b32_e32 v51, v82
	v_mov_b32_e32 v52, v82
	v_mov_b32_e32 v53, v82
	v_mov_b32_e32 v46, v82
	v_mov_b32_e32 v47, v82
	v_mov_b32_e32 v48, v82
	v_mov_b32_e32 v49, v82
	v_mov_b32_e32 v42, v82
	v_mov_b32_e32 v43, v82
	v_mov_b32_e32 v44, v82
	v_mov_b32_e32 v45, v82
	v_mov_b32_e32 v38, v82
	v_mov_b32_e32 v39, v82
	v_mov_b32_e32 v40, v82
	v_mov_b32_e32 v41, v82
	v_mov_b32_e32 v34, v82
	v_mov_b32_e32 v35, v82
	v_mov_b32_e32 v36, v82
	v_mov_b32_e32 v37, v82
	s_waitcnt lgkmcnt(0)
	s_barrier
	s_waitcnt vmcnt(0)
	s_branch .LBB0_1302

.Lbar_noinv_11:
	s_waitcnt lgkmcnt(0)
	s_barrier
.LBB0_1419:
	v_mov_b32_e32 v1, v0
	s_mov_b32 s2, s10
	s_waitcnt vmcnt(0)
	v_ashrrev_i32_e32 v2, 8, v1
	s_movk_i32 s3, 0x1f71
	v_lshl_add_u32 v1, s2, 1, v2
	v_cmp_gt_i32_e32 vcc, s3, v1
	s_and_saveexec_b64 s[8:9], vcc
	s_cbranch_execz .LBB0_1466
	s_load_dword s3, s[0:1], 0xe0
	s_load_dwordx4 s[4:7], s[16:17], 0xc8
	v_lshlrev_b32_e32 v2, 3, v2
	v_lshl_add_u32 v37, s2, 4, v2
	v_mbcnt_lo_u32_b32 v2, -1, 0
	s_waitcnt lgkmcnt(0)
	s_lshl_b32 s11, s3, 1
	s_add_u32 s14, s6, 0x4000
	s_addc_u32 s15, s7, 0
	s_add_u32 s20, s6, 0x17f0000
	s_addc_u32 s21, s7, 0
	s_add_u32 s22, s6, 0x4a0000
	s_addc_u32 s23, s7, 0
	s_add_u32 s24, s6, 0x1270000
	s_addc_u32 s25, s7, 0
	s_add_u32 s26, s6, 0x770000
	s_addc_u32 s27, s7, 0
	s_add_u32 s28, s6, 0x570000
	s_addc_u32 s29, s7, 0
	s_add_u32 s30, s6, 0x530000
	s_addc_u32 s31, s7, 0
	s_add_u32 s34, s6, 0x4d0000
	s_addc_u32 s35, s7, 0
	v_mbcnt_hi_u32_b32 v46, -1, v2
	s_add_u32 s6, s6, 0x50000
	v_and_b32_e32 v2, 64, v46
	s_addc_u32 s7, s7, 0
	s_lshl_b32 s33, s3, 4
	s_mov_b64 s[36:37], 0
	s_movk_i32 s41, 0x7ff
	s_movk_i32 s66, 0x44f
	s_movk_i32 s67, 0x4af
	s_movk_i32 s68, 0x4ef
	s_movk_i32 s69, 0x6ef
	s_movk_i32 s70, 0xc6f
	s_movk_i32 s71, 0x11ef
	s_movk_i32 s72, 0x176f
	v_mov_b32_e32 v35, 0
	s_movk_i32 s73, 0x1000
	s_movk_i32 s74, 0x1800
	s_movk_i32 s75, 0x1c0
	s_movk_i32 s76, 0x1fff
	s_mov_b64 s[38:39], 0x1000
	s_mov_b32 s40, 0x3a800000
	s_mov_b32 s77, 0x800000
	s_movk_i32 s78, 0x1f70
	v_mov_b32_e32 v44, 0x9000
	v_mov_b32_e32 v45, 0x7800
	v_add_u32_e32 v47, 64, v2
	v_mov_b32_e32 v36, 0x358637bd
	s_branch .LBB0_1422

.Lbar_noinv_12:
	s_waitcnt lgkmcnt(0)
	s_barrier
.LBB0_1524:
	s_mov_b32 s98, 0
	v_mov_b32_e32 v255, 0x0
	v_bfe_u32 v1, v0, 0, 1
	v_lshlrev_b32_e32 v1, 7, v1
	v_xor_b32_e32 v255, v255, v1
	v_bfe_u32 v1, v0, 1, 3
	v_mul_u32_u24_e32 v1, 0x110, v1
	v_xor_b32_e32 v255, v255, v1
	v_bfe_u32 v1, v0, 4, 2
	v_lshlrev_b32_e32 v1, 4, v1
	v_xor_b32_e32 v255, v255, v1
	v_bfe_u32 v1, v0, 8, 1
	v_lshlrev_b32_e32 v1, 14, v1
	v_xor_b32_e32 v255, v255, v1
	v_add_u32_e32 v254, 0x10000, v255
	v_xor_b32_e32 v253, 0x880, v255
	v_xor_b32_e32 v252, 0x10880, v255
	v_mov_b32_e32 v251, 0x8000
	v_bfe_u32 v1, v0, 1, 3
	v_lshlrev_b32_e32 v1, 8, v1
	v_add_u32_e32 v251, v251, v1
	v_bfe_u32 v1, v0, 6, 2
	v_mul_u32_u24_e32 v1, 0x1800, v1
	v_add_u32_e32 v251, v251, v1
	v_mov_b32_e32 v2, 0x0
	v_bfe_u32 v1, v0, 0, 1
	v_lshlrev_b32_e32 v1, 7, v1
	v_xor_b32_e32 v2, v2, v1
	v_bfe_u32 v1, v0, 1, 3
	v_lshlrev_b32_e32 v1, 4, v1
	v_xor_b32_e32 v2, v2, v1
	v_bfe_u32 v1, v0, 4, 2
	v_lshlrev_b32_e32 v1, 4, v1
	v_xor_b32_e32 v2, v2, v1
	v_bfe_u32 v1, v0, 6, 1
	v_lshlrev_b32_e32 v1, 7, v1
	v_xor_b32_e32 v2, v2, v1
	v_add_u32_e32 v251, v251, v2
	v_add_u32_e32 v250, 0x10000, v251
	v_mov_b32_e32 v249, 0x8800
	v_bfe_u32 v1, v0, 1, 3
	v_lshlrev_b32_e32 v1, 8, v1
	v_add_u32_e32 v249, v249, v1
	v_bfe_u32 v1, v0, 6, 2
	v_mul_u32_u24_e32 v1, 0x1800, v1
	v_add_u32_e32 v249, v249, v1
	v_mov_b32_e32 v2, 0x80
	v_bfe_u32 v1, v0, 0, 1
	v_lshlrev_b32_e32 v1, 7, v1
	v_xor_b32_e32 v2, v2, v1
	v_bfe_u32 v1, v0, 1, 3
	v_lshlrev_b32_e32 v1, 4, v1
	v_xor_b32_e32 v2, v2, v1
	v_bfe_u32 v1, v0, 4, 2
	v_lshlrev_b32_e32 v1, 4, v1
	v_xor_b32_e32 v2, v2, v1
	v_bfe_u32 v1, v0, 6, 1
	v_lshlrev_b32_e32 v1, 7, v1
	v_xor_b32_e32 v2, v2, v1
	v_add_u32_e32 v249, v249, v2
	v_add_u32_e32 v248, 0x10000, v249
	v_xor_b32_e32 v247, 0x40, v255
	v_xor_b32_e32 v246, 0x10040, v255
	v_xor_b32_e32 v245, 0x8c0, v255
	v_xor_b32_e32 v244, 0x108c0, v255
	v_xor_b32_e32 v243, 0x40, v251
	v_xor_b32_e32 v242, 0x10040, v251
	v_xor_b32_e32 v241, 0x40, v249
	v_xor_b32_e32 v240, 0x10040, v249
	v_mov_b32_e32 v239, 0x0
	v_bfe_u32 v1, v0, 0, 4
	v_lshlrev_b32_e32 v1, 4, v1
	v_xor_b32_e32 v239, v239, v1
	v_bfe_u32 v1, v0, 4, 4
	v_mul_u32_u24_e32 v1, 0x110, v1
	v_xor_b32_e32 v239, v239, v1
	v_bfe_u32 v1, v0, 8, 1
	v_lshlrev_b32_e32 v1, 12, v1
	v_xor_b32_e32 v239, v239, v1
	v_add_u32_e32 v238, 0x10000, v239
	v_mov_b32_e32 v237, 0x0
	v_bfe_u32 v1, v0, 0, 3
	v_lshlrev_b32_e32 v1, 4, v1
	v_add_u32_e32 v237, v237, v1
	v_bfe_u32 v1, v0, 3, 6
	v_lshlrev_b32_e32 v1, 11, v1
	v_add_u32_e32 v237, v237, v1
	v_add_u32_e32 v236, 0x20000, v237
	v_add_u32_e32 v235, 0x40000, v237
	v_add_u32_e32 v234, 0x60000, v237
	v_mov_b32_e32 v1, v0
	s_load_dword s2, s[0:1], 0xe0
	s_mov_b32 s3, s10
	v_mov_b32_e32 v1, v0
	s_waitcnt lgkmcnt(0)
	s_lshr_b32 s11, s2, 3
	s_waitcnt vmcnt(0)
	v_cvt_f32_u32_e32 v2, s11
	s_mov_b32 s2, s10
	s_ashr_i32 s3, s2, 3
	v_rcp_iflag_f32_e32 v2, v2
	s_ashr_i32 s4, s2, 31
	s_sub_i32 s2, 0, s11
	s_abs_i32 s3, s3
	v_mul_f32_e32 v1, 0x4f7ffffe, v2
	v_cvt_u32_f32_e32 v1, v1
	s_mov_b32 s45, 0
	v_readfirstlane_b32 s5, v1
	s_mul_i32 s2, s2, s5
	s_mul_hi_u32 s2, s5, s2
	s_add_i32 s2, s5, s2
	s_mul_hi_u32 s5, s3, s2
	s_mul_i32 s5, s5, s11
	s_sub_i32 s3, s3, s5
	s_sub_i32 s5, s3, s11
	s_cmp_ge_u32 s3, s11
	s_cselect_b32 s3, s5, s3
	s_sub_i32 s5, s3, s11
	s_cmp_ge_u32 s3, s11
	s_cselect_b32 s3, s5, s3
	s_xor_b32 s3, s3, s4
	s_sub_i32 s24, s3, s4
	s_mov_b32 s3, s10
	s_cmpk_gt_i32 s24, 0x5f
	s_cbranch_scc1 .LBB0_1604
	s_load_dwordx2 s[4:5], s[16:17], 0xd0
	s_mov_b32 s3, s10
	v_mov_b32_e32 v54, 0
	v_mov_b32_e32 v1, v0
	s_waitcnt lgkmcnt(0)
	s_add_u32 s25, s4, 0x17f0000
	s_addc_u32 s26, s5, 0
	s_add_u32 s8, s4, 0x37f0000
	s_addc_u32 s9, s5, 0
	s_add_u32 s27, s4, 0x50000
	s_addc_u32 s28, s5, 0
	s_ashr_i32 s4, s24, 31
	s_lshr_b32 s4, s4, 27
	s_add_i32 s4, s24, s4
	s_ashr_i32 s4, s4, 5
	s_lshl_b32 s5, s24, 1
	s_lshl_b32 s12, s4, 6
	s_sub_i32 s5, s5, s12
	s_lshl_b32 s4, s4, 2
	s_and_b32 s12, s24, 3
	s_or_b32 s29, s4, s12
	s_sub_i32 s4, s11, s24
	s_addk_i32 s4, 0x5f
	s_mul_hi_u32 s2, s4, s2
	s_mul_i32 s12, s2, s11
	s_sub_i32 s4, s4, s12
	s_add_i32 s12, s2, 1
	s_sub_i32 s13, s4, s11
	s_cmp_ge_u32 s4, s11
	s_cselect_b32 s2, s12, s2
	s_cselect_b32 s4, s13, s4
	s_add_i32 s12, s2, 1
	s_cmp_ge_u32 s4, s11
	s_cselect_b32 s2, s12, s2
	s_and_b32 s3, s3, 7
	s_and_b32 s4, s5, -8
	s_lshl_b32 s30, s2, 4
	s_mul_i32 s2, s29, 0xc0
	s_or_b32 s31, s3, s4
	s_ashr_i32 s3, s2, 31
	s_lshl_b64 s[2:3], s[2:3], 11
	v_lshlrev_b32_e32 v2, 8, v1
	v_lshlrev_b32_e32 v1, 4, v1
	s_add_u32 s2, s27, s2
	v_and_b32_e32 v1, 0x70, v1
	s_movk_i32 s33, 0xf800
	v_mov_b32_e32 v175, 0
	s_addc_u32 s3, s28, s3
	v_and_or_b32 v174, v2, s33, v1
	s_lshl_b32 s4, s31, 8
	v_lshl_add_u64 v[2:3], s[2:3], 0, v[174:175]
	s_mov_b32 s12, 0x40000
	s_ashr_i32 s5, s4, 31
	v_add_co_u32_e32 v14, vcc, s12, v2
	s_lshl_b64 s[4:5], s[4:5], 11
	s_nop 0
	v_addc_co_u32_e32 v15, vcc, 0, v3, vcc
	s_mov_b32 s34, 0x20000
	s_add_u32 s4, s25, s4
	v_add_co_u32_e32 v16, vcc, s34, v2
	s_addc_u32 s5, s26, s5
	s_nop 0
	v_addc_co_u32_e32 v17, vcc, 0, v3, vcc
	global_load_dwordx4 v[2:5], v[14:15], off
	global_load_dwordx4 v[6:9], v[16:17], off
	global_load_dwordx4 v[10:13], v174, s[2:3]
	v_lshl_add_u64 v[14:15], s[4:5], 0, v[174:175]
	s_mov_b32 s13, 0x60000
	v_add_co_u32_e32 v30, vcc, s13, v14
	v_mov_b32_e32 v1, v0
	s_nop 0
	v_addc_co_u32_e32 v31, vcc, 0, v15, vcc
	v_add_co_u32_e32 v32, vcc, s12, v14
	s_movk_i32 s36, 0xf0
	s_nop 0
	v_addc_co_u32_e32 v33, vcc, 0, v15, vcc
	v_add_co_u32_e32 v34, vcc, s34, v14
	s_mov_b32 s35, 2
	s_nop 0
	v_addc_co_u32_e32 v35, vcc, 0, v15, vcc
	global_load_dwordx4 v[14:17], v174, s[4:5]
	global_load_dwordx4 v[18:21], v[34:35], off
	global_load_dwordx4 v[22:25], v[32:33], off
	global_load_dwordx4 v[26:29], v[30:31], off
	v_mov_b32_e32 v30, v0
	v_ashrrev_i32_e32 v31, 4, v1
	v_xor_b32_e32 v1, v31, v1
	v_lshlrev_b32_e32 v31, 8, v31
	v_lshlrev_b32_e32 v1, 4, v1
	v_and_or_b32 v1, v1, s36, v31
	s_movk_i32 s37, 0xff80
	s_mov_b32 s38, 0x10000
	s_mov_b32 s39, 0x18000
	s_movk_i32 s40, 0x8a0
	s_movk_i32 s41, 0x1140
	v_mov_b32_e32 v176, 0x18000
	s_mov_b32 s22, 2
	s_mov_b32 s42, s24
	s_mov_b32 s43, s29
	s_mov_b32 s44, s31
	v_mov_b32_e32 v55, v54
	v_mov_b32_e32 v56, v54
	v_mov_b32_e32 v57, v54
	v_mov_b32_e32 v82, v54
	v_mov_b32_e32 v83, v54
	v_mov_b32_e32 v84, v54
	v_mov_b32_e32 v85, v54
	v_mov_b32_e32 v86, v54
	v_mov_b32_e32 v87, v54
	v_mov_b32_e32 v88, v54
	v_mov_b32_e32 v89, v54
	v_mov_b32_e32 v90, v54
	v_mov_b32_e32 v91, v54
	v_mov_b32_e32 v92, v54
	v_mov_b32_e32 v93, v54
	v_mov_b32_e32 v94, v54
	v_mov_b32_e32 v95, v54
	v_mov_b32_e32 v96, v54
	v_mov_b32_e32 v97, v54
	s_waitcnt vmcnt(4)
	ds_write_b128 v1, v[10:13] offset:32768
	ds_write_b128 v1, v[6:9] offset:40960
	ds_write_b128 v1, v[2:5] offset:49152
	s_waitcnt vmcnt(3)
	ds_write_b128 v1, v[14:17]
	s_waitcnt vmcnt(2)
	ds_write_b128 v1, v[18:21] offset:8192
	s_waitcnt vmcnt(1)
	ds_write_b128 v1, v[22:25] offset:16384
	s_waitcnt vmcnt(0)
	ds_write_b128 v1, v[26:29] offset:24576
	v_mov_b32_e32 v98, v54
	v_lshlrev_b32_e32 v2, 4, v30
	v_lshlrev_b32_e32 v1, 8, v30
	v_and_b32_e32 v2, 0x70, v2
	v_and_or_b32 v174, v1, s33, v2
	v_lshl_add_u64 v[2:3], s[2:3], 0, v[174:175]
	v_add_co_u32_e32 v10, vcc, s12, v2
	v_mov_b32_e32 v1, 0x10000
	s_nop 0
	v_addc_co_u32_e32 v11, vcc, 0, v3, vcc
	v_add_co_u32_e32 v12, vcc, s34, v2
	v_mov_b32_e32 v99, v54
	s_nop 0
	v_addc_co_u32_e32 v13, vcc, 0, v3, vcc
	global_load_dwordx4 v[2:5], v[10:11], off offset:128
	global_load_dwordx4 v[6:9], v[12:13], off offset:128
	v_lshl_add_u64 v[10:11], s[4:5], 0, v[174:175]
	v_add_co_u32_e32 v12, vcc, s13, v10
	v_mov_b32_e32 v100, v54
	s_nop 0
	v_addc_co_u32_e32 v13, vcc, 0, v11, vcc
	v_add_co_u32_e32 v22, vcc, s12, v10
	v_mov_b32_e32 v101, v54
	s_nop 0
	v_addc_co_u32_e32 v23, vcc, 0, v11, vcc
	v_add_co_u32_e32 v30, vcc, s34, v10
	global_load_dwordx4 v[14:17], v[12:13], off offset:128
	global_load_dwordx4 v[18:21], v[22:23], off offset:128
	v_addc_co_u32_e32 v31, vcc, 0, v11, vcc
	global_load_dwordx4 v[10:13], v174, s[2:3] offset:128
	global_load_dwordx4 v[22:25], v[30:31], off offset:128
	global_load_dwordx4 v[26:29], v174, s[4:5] offset:128
	v_mov_b32_e32 v102, v54
	v_mov_b32_e32 v103, v54
	v_mov_b32_e32 v104, v54
	v_mov_b32_e32 v105, v54
	v_mov_b32_e32 v106, v54
	v_mov_b32_e32 v107, v54
	v_mov_b32_e32 v108, v54
	v_mov_b32_e32 v109, v54
	v_mov_b32_e32 v110, v54
	v_mov_b32_e32 v111, v54
	v_mov_b32_e32 v112, v54
	v_mov_b32_e32 v113, v54
	v_mov_b32_e32 v114, v54
	v_mov_b32_e32 v115, v54
	v_mov_b32_e32 v116, v54
	v_mov_b32_e32 v117, v54
	v_mov_b32_e32 v118, v54
	v_mov_b32_e32 v119, v54
	v_mov_b32_e32 v120, v54
	v_mov_b32_e32 v121, v54
	v_mov_b32_e32 v122, v54
	v_mov_b32_e32 v123, v54
	v_mov_b32_e32 v124, v54
	v_mov_b32_e32 v125, v54
	v_mov_b32_e32 v78, v54
	v_mov_b32_e32 v79, v54
	v_mov_b32_e32 v80, v54
	v_mov_b32_e32 v81, v54
	v_mov_b32_e32 v74, v54
	v_mov_b32_e32 v75, v54
	v_mov_b32_e32 v76, v54
	v_mov_b32_e32 v77, v54
	v_mov_b32_e32 v70, v54
	v_mov_b32_e32 v71, v54
	v_mov_b32_e32 v72, v54
	v_mov_b32_e32 v73, v54
	v_mov_b32_e32 v66, v54
	v_mov_b32_e32 v67, v54
	v_mov_b32_e32 v68, v54
	v_mov_b32_e32 v69, v54
	v_mov_b32_e32 v62, v54
	v_mov_b32_e32 v63, v54
	v_mov_b32_e32 v64, v54
	v_mov_b32_e32 v65, v54
	v_mov_b32_e32 v58, v54
	v_mov_b32_e32 v59, v54
	v_mov_b32_e32 v60, v54
	v_mov_b32_e32 v61, v54
	v_mov_b32_e32 v50, v54
	v_mov_b32_e32 v51, v54
	v_mov_b32_e32 v52, v54
	v_mov_b32_e32 v53, v54
	v_mov_b32_e32 v46, v54
	v_mov_b32_e32 v47, v54
	v_mov_b32_e32 v48, v54
	v_mov_b32_e32 v49, v54
	v_mov_b32_e32 v42, v54
	v_mov_b32_e32 v43, v54
	v_mov_b32_e32 v44, v54
	v_mov_b32_e32 v45, v54
	v_mov_b32_e32 v38, v54
	v_mov_b32_e32 v39, v54
	v_mov_b32_e32 v40, v54
	v_mov_b32_e32 v41, v54
	v_mov_b32_e32 v34, v54
	v_mov_b32_e32 v35, v54
	v_mov_b32_e32 v36, v54
	v_mov_b32_e32 v37, v54
	v_mov_b32_e32 v30, v54
	v_mov_b32_e32 v31, v54
	v_mov_b32_e32 v32, v54
	v_mov_b32_e32 v33, v54
	s_waitcnt lgkmcnt(0)
	s_barrier
	s_waitcnt vmcnt(0)
	s_branch .LBB0_1528

.Lbar_noinv_13:
	s_waitcnt lgkmcnt(0)
	s_barrier
.LBB0_1661:
	s_waitcnt vmcnt(0)
	v_mov_b32_e32 v2, v0
	s_mov_b32 s2, s10
	v_ashrrev_i32_e32 v3, 8, v2
	s_movk_i32 s3, 0x200
	v_lshl_add_u32 v1, s2, 1, v3
	v_cmp_gt_i32_e32 vcc, s3, v1
	s_and_saveexec_b64 s[8:9], vcc
	s_cbranch_execz .LBB0_1678
	s_load_dword s3, s[0:1], 0xe0
	s_load_dwordx4 s[12:15], s[16:17], 0xc8
	v_lshrrev_b32_e32 v2, 8, v2
	v_mul_i32_i24_e32 v48, 0x10800, v3
	s_mov_b64 s[30:31], 0
	s_waitcnt lgkmcnt(0)
	s_lshl_b32 s11, s3, 1
	s_add_u32 s22, s14, 0x37f0000
	s_addc_u32 s23, s15, 0
	s_add_u32 s24, s14, 0x7cf0000
	s_addc_u32 s25, s15, 0
	s_add_u32 s26, s14, 0xd4b0000
	s_addc_u32 s27, s15, 0
	s_lshl_b32 s2, s2, 1
	v_add_u16_e32 v49, s2, v2
	s_add_u32 s28, s12, 0x4800000
	v_mbcnt_lo_u32_b32 v2, -1, 0
	s_addc_u32 s29, s13, 0
	v_mbcnt_hi_u32_b32 v53, -1, v2
	s_add_u32 s12, s12, 0x4000000
	v_and_b32_e32 v2, 64, v53
	s_addc_u32 s13, s13, 0
	s_mov_b32 s33, 0xbfb8aa3b
	s_mov_b32 s52, 0x42ce8ed0
	s_mov_b32 s53, 0xc2b17218
	s_mov_b32 s54, 0x7f800000
	v_mov_b32_e32 v50, 0x7f800000
	s_mov_b32 s55, 0x3f2aaaab
	v_mov_b32_e32 v51, 0x3ecc95a3
	s_mov_b32 s56, 0x3f317218
	s_mov_b32 s57, 0x33800000
	v_mov_b32_e32 v3, 0
	s_movk_i32 s58, 0x1140
	s_mov_b32 s59, 0x3fb8aa3b
	s_mov_b32 s60, 0xc2ce8ed0
	s_mov_b32 s61, 0x42b17218
	s_mov_b64 s[34:35], 0x1000
	s_mov_b64 s[36:37], 0x1400
	s_movk_i32 s62, 0x100
	v_mov_b64_e32 v[4:5], 0x40000
	s_mov_b64 s[38:39], 0x37f0200
	s_mov_b64 s[40:41], 0x37f0300
	v_mov_b32_e32 v52, 0x358637bd
	s_mov_b32 s63, 0x800000
	s_movk_i32 s64, 0x1fff
	s_mov_b32 s65, 0x17f0000
	s_mov_b64 s[42:43], 0x80
	s_mov_b64 s[44:45], 0x200
	s_mov_b64 s[46:47], 0x800
	s_mov_b64 s[48:49], 0x1140
	s_movk_i32 s66, 0xfe
	s_movk_i32 s67, 0x900
	s_movk_i32 s68, 0x110
	s_movk_i32 s69, 0x4000
	s_movk_i32 s70, 0x1ff
	v_add_u32_e32 v54, 64, v2
	v_xor_b32_e32 v55, 32, v53
	v_xor_b32_e32 v56, 16, v53
	v_xor_b32_e32 v57, 8, v53
	v_xor_b32_e32 v58, 4, v53
	v_xor_b32_e32 v59, 2, v53
	v_xor_b32_e32 v60, 1, v53
	v_mov_b32_e32 v61, 7
	s_branch .LBB0_1664

.Lbar_noinv_14:
	s_waitcnt lgkmcnt(0)
	s_barrier
.LBB0_1736:
	v_mov_b32_e32 v1, v0
	s_mov_b32 s3, s10
	s_load_dword s2, s[0:1], 0xe0
	s_load_dwordx2 s[12:13], s[16:17], 0xd0
	s_waitcnt vmcnt(0)
	v_mov_b32_e32 v2, v0
	s_waitcnt lgkmcnt(0)
	s_add_u32 s14, s12, 0x37f0000
	s_addc_u32 s15, s13, 0
	s_lshr_b32 s11, s2, 3
	v_cvt_f32_u32_e32 v1, s11
	s_sub_i32 s4, 0, s11
	s_mov_b32 s2, s10
	v_rcp_iflag_f32_e32 v1, v1
	s_ashr_i32 s3, s2, 3
	s_abs_i32 s3, s3
	s_ashr_i32 s2, s2, 31
	v_mul_f32_e32 v1, 0x4f7ffffe, v1
	v_cvt_u32_f32_e32 v1, v1
	s_nop 0
	v_readfirstlane_b32 s33, v1
	s_mul_i32 s4, s4, s33
	s_mul_hi_u32 s4, s33, s4
	s_add_i32 s33, s33, s4
	s_mul_hi_u32 s4, s3, s33
	s_mul_i32 s4, s4, s11
	s_sub_i32 s3, s3, s4
	s_sub_i32 s4, s3, s11
	s_cmp_ge_u32 s3, s11
	s_cselect_b32 s3, s4, s3
	s_sub_i32 s4, s3, s11
	s_cmp_ge_u32 s3, s11
	s_cselect_b32 s3, s4, s3
	s_xor_b32 s3, s3, s2
	s_sub_i32 s26, s3, s2
	s_mov_b32 s2, s10
	s_cmp_gt_i32 s26, 23
	s_cbranch_scc1 .LBB0_1836
	s_mov_b32 s5, s10
	s_cmpk_gt_i32 s26, 0xffe0
	s_cbranch_scc0 .LBB0_1739
	s_bfe_i32 s2, s26, 0x80000
	s_mulk_i32 s2, 0x56
	s_bfe_u32 s3, s2, 0x1000f
	s_bfe_u32 s2, s2, 0x80008
	s_add_i32 s2, s2, s3
	s_sext_i32_i8 s3, s2
	s_mul_i32 s2, s2, 3
	s_sub_i32 s2, s26, s2
	s_lshl_b32 s4, s3, 3
	s_sext_i32_i8 s27, s2
	s_mov_b32 s45, 1
	s_cbranch_execz .LBB0_1740
	s_branch .LBB0_1741

.Lbar_noinv_15:
	s_waitcnt lgkmcnt(0)
	s_barrier
.LBB0_2017:
	s_waitcnt vmcnt(0)
	v_mov_b32_e32 v3, v0
	s_mov_b32 s2, s10
	v_ashrrev_i32_e32 v2, 8, v3
	s_movk_i32 s11, 0x600
	v_lshl_add_u32 v1, s2, 1, v2
	v_cmp_gt_i32_e32 vcc, s11, v1
	s_and_saveexec_b64 s[22:23], vcc
	s_cbranch_execz .LBB0_2141
	s_load_dword s3, s[0:1], 0xe0
	s_load_dwordx4 s[12:15], s[16:17], 0xc8
	v_lshrrev_b32_e32 v3, 8, v3
	s_mov_b32 s4, 0x10800
	v_mul_i32_i24_e32 v161, 0x10800, v2
	s_waitcnt lgkmcnt(0)
	s_lshl_b32 s33, s3, 1
	s_add_u32 s24, s14, 0x17f0000
	s_addc_u32 s25, s15, 0
	s_add_u32 s26, s14, 0xc3b0000
	s_addc_u32 s27, s15, 0
	s_add_u32 s28, s14, 0x8130000
	s_addc_u32 s29, s15, 0
	s_add_u32 s30, s14, 0xaa30000
	s_addc_u32 s31, s15, 0
	s_add_u32 s34, s14, 0x40000
	s_addc_u32 s35, s15, 0
	s_add_u32 s36, s14, 0x37f0000
	s_addc_u32 s37, s15, 0
	s_add_u32 s40, s14, 0xd4b0000
	s_addc_u32 s41, s15, 0
	s_add_u32 s12, s12, 0x4a00000
	s_addc_u32 s13, s13, 0
	s_lshl_b32 s2, s2, 1
	v_add_u16_e32 v169, s2, v3
	v_mov_b32_e32 v3, 0x4800
	v_mad_i32_i24 v173, v2, s4, v3
	s_mov_b32 s44, 0x358637bd
	v_mbcnt_lo_u32_b32 v2, -1, 0
	v_mbcnt_hi_u32_b32 v177, -1, v2
	s_mov_b32 s54, 0xfff80000
	v_and_b32_e32 v2, 64, v177
	s_mov_b64 s[38:39], 0xd4b0000
	s_mov_b64 s[42:43], 0
	s_movk_i32 s70, 0x200
	s_movk_i32 s71, 0x60
	v_mov_b32_e32 v3, 0
	s_mov_b32 s45, 0x3c2aaaab
	s_mov_b32 s72, 0x800000
	s_mov_b32 s73, 0x8800
	s_movk_i32 s74, 0xab
	s_movk_i32 s75, 0x100
	s_movk_i32 s76, 0x88
	s_movk_i32 s77, 0x3400
	s_mov_b64 s[46:47], 0x18000
	s_mov_b64 s[48:49], 0x30000
	s_mov_b32 s78, 0x8a00
	s_mov_b32 s79, 0xe000
	s_movk_i32 s80, 0x8a0
	s_movk_i32 s81, 0x70
	s_mov_b32 s82, 0xbfb8aa3b
	s_mov_b32 s83, 0x42ce8ed0
	s_mov_b32 s84, 0xc2b17218
	s_mov_b32 s85, 0x7f800000
	s_mov_b32 s86, 0x3f2aaaab
	v_mov_b32_e32 v174, 0x3ecc95a3
	s_mov_b32 s87, 0x3f317218
	s_mov_b32 s88, 0x33800000
	s_mov_b32 s89, 0x3fb8aa3b
	s_mov_b32 s90, 0xc2ce8ed0
	s_mov_b32 s91, 0x42b17218
	s_mov_b32 s93, 0xd4b0000
	s_mov_b64 s[50:51], 0x80000
	s_mov_b64 s[52:53], 0xd4b4000
	s_mov_b32 s94, 0xd4b4000
	s_mov_b32 s55, -1
	s_mov_b64 s[56:57], 0x20000
	s_mov_b64 s[58:59], 0x4000
	s_movk_i32 s95, 0x1140
	v_mov_b32_e32 v175, 0x358637bd
	s_mov_b64 s[60:61], 0x17f0600
	s_mov_b32 s96, 0x17f0000
	s_movk_i32 s97, 0x5ff
	v_mov_b32_e32 v176, 0x2000
	v_xor_b32_e32 v178, 32, v177
	v_add_u32_e32 v179, 64, v2
	v_mov_b32_e32 v180, 4
	v_mov_b32_e32 v181, 0x70
	v_mov_b32_e32 v182, 0x7f800000
	v_mov_b32_e32 v183, 6
	v_mov_b32_e32 v184, 1
	s_branch .LBB0_2021

.Lbar_noinv_16:
	s_waitcnt lgkmcnt(0)
	s_barrier
.LBB0_2199:
	s_mov_b32 s98, 0
	v_mov_b32_e32 v255, 0x0
	v_bfe_u32 v1, v0, 0, 1
	v_lshlrev_b32_e32 v1, 7, v1
	v_xor_b32_e32 v255, v255, v1
	v_bfe_u32 v1, v0, 1, 3
	v_mul_u32_u24_e32 v1, 0x110, v1
	v_xor_b32_e32 v255, v255, v1
	v_bfe_u32 v1, v0, 4, 2
	v_lshlrev_b32_e32 v1, 4, v1
	v_xor_b32_e32 v255, v255, v1
	v_bfe_u32 v1, v0, 8, 1
	v_lshlrev_b32_e32 v1, 14, v1
	v_xor_b32_e32 v255, v255, v1
	v_add_u32_e32 v254, 0x10000, v255
	v_xor_b32_e32 v253, 0x880, v255
	v_xor_b32_e32 v252, 0x10880, v255
	v_mov_b32_e32 v251, 0x8000
	v_bfe_u32 v1, v0, 0, 1
	v_lshlrev_b32_e32 v1, 7, v1
	v_xor_b32_e32 v251, v251, v1
	v_bfe_u32 v1, v0, 1, 3
	v_mul_u32_u24_e32 v1, 0x110, v1
	v_xor_b32_e32 v251, v251, v1
	v_bfe_u32 v1, v0, 4, 2
	v_lshlrev_b32_e32 v1, 4, v1
	v_xor_b32_e32 v251, v251, v1
	v_bfe_u32 v1, v0, 6, 2
	v_lshlrev_b32_e32 v1, 13, v1
	v_xor_b32_e32 v251, v251, v1
	v_add_u32_e32 v250, 0x10000, v251
	v_xor_b32_e32 v249, 0x880, v251
	v_xor_b32_e32 v248, 0x10880, v251
	v_xor_b32_e32 v247, 0x40, v255
	v_xor_b32_e32 v246, 0x10040, v255
	v_xor_b32_e32 v245, 0x8c0, v255
	v_xor_b32_e32 v244, 0x108c0, v255
	v_xor_b32_e32 v243, 0x40, v251
	v_xor_b32_e32 v242, 0x10040, v251
	v_xor_b32_e32 v241, 0x8c0, v251
	v_xor_b32_e32 v237, 0x108c0, v251
	v_mov_b32_e32 v236, 0x0
	v_bfe_u32 v1, v0, 0, 4
	v_lshlrev_b32_e32 v1, 4, v1
	v_xor_b32_e32 v236, v236, v1
	v_bfe_u32 v1, v0, 4, 4
	v_mul_u32_u24_e32 v1, 0x110, v1
	v_xor_b32_e32 v236, v236, v1
	v_bfe_u32 v1, v0, 8, 1
	v_lshlrev_b32_e32 v1, 12, v1
	v_xor_b32_e32 v236, v236, v1
	v_add_u32_e32 v235, 0x10000, v236
	v_mov_b32_e32 v234, 0x0
	v_bfe_u32 v1, v0, 0, 3
	v_lshlrev_b32_e32 v1, 4, v1
	v_add_u32_e32 v234, v234, v1
	v_bfe_u32 v1, v0, 3, 6
	v_lshlrev_b32_e32 v1, 11, v1
	v_add_u32_e32 v234, v234, v1
	v_add_u32_e32 v233, 0x20000, v234
	v_add_u32_e32 v232, 0x40000, v234
	v_add_u32_e32 v231, 0x60000, v234
	v_mov_b32_e32 v1, v0
	s_load_dword s2, s[0:1], 0xe0
	s_mov_b32 s3, s10
	v_mov_b32_e32 v1, v0
	s_waitcnt lgkmcnt(0)
	s_lshr_b32 s11, s2, 3
	s_waitcnt vmcnt(0)
	v_cvt_f32_u32_e32 v2, s11
	s_mov_b32 s2, s10
	s_ashr_i32 s3, s2, 3
	v_rcp_iflag_f32_e32 v2, v2
	s_ashr_i32 s4, s2, 31
	s_sub_i32 s2, 0, s11
	s_abs_i32 s3, s3
	v_mul_f32_e32 v1, 0x4f7ffffe, v2
	v_cvt_u32_f32_e32 v1, v1
	s_mov_b32 s50, 0
	v_readfirstlane_b32 s5, v1
	s_mul_i32 s2, s2, s5
	s_mul_hi_u32 s2, s5, s2
	s_add_i32 s2, s5, s2
	s_mul_hi_u32 s5, s3, s2
	s_mul_i32 s5, s5, s11
	s_sub_i32 s3, s3, s5
	s_sub_i32 s5, s3, s11
	s_cmp_ge_u32 s3, s11
	s_cselect_b32 s3, s5, s3
	s_sub_i32 s5, s3, s11
	s_cmp_ge_u32 s3, s11
	s_cselect_b32 s3, s5, s3
	s_xor_b32 s3, s3, s4
	s_sub_i32 s28, s3, s4
	s_mov_b32 s3, s10
	s_cmp_gt_i32 s28, 31
	s_cbranch_scc1 .LBB0_2263
	s_load_dwordx4 s[4:7], s[16:17], 0xc8
	s_mov_b32 s3, s10
	v_mov_b32_e32 v82, 0
	v_mov_b32_e32 v1, v0
	s_waitcnt lgkmcnt(0)
	s_add_u32 s29, s6, 0x17f0000
	s_addc_u32 s30, s7, 0
	s_add_u32 s12, s4, 0x2000000
	s_addc_u32 s13, s5, 0
	s_add_u32 s14, s6, 0x24000
	s_addc_u32 s15, s7, 0
	s_add_u32 s31, s6, 0x570000
	s_addc_u32 s33, s7, 0
	s_ashr_i32 s6, s28, 31
	s_lshr_b32 s6, s6, 27
	s_add_i32 s6, s28, s6
	s_ashr_i32 s6, s6, 5
	s_lshl_b32 s7, s28, 1
	s_lshl_b32 s20, s6, 6
	s_sub_i32 s7, s7, s20
	s_lshl_b32 s6, s6, 2
	s_and_b32 s20, s28, 3
	s_or_b32 s34, s6, s20
	s_sub_i32 s6, s11, s28
	s_add_i32 s6, s6, 31
	s_mul_hi_u32 s2, s6, s2
	s_mul_i32 s20, s2, s11
	s_sub_i32 s6, s6, s20
	s_add_i32 s20, s2, 1
	s_sub_i32 s21, s6, s11
	s_cmp_ge_u32 s6, s11
	s_cselect_b32 s2, s20, s2
	s_cselect_b32 s6, s21, s6
	s_add_i32 s20, s2, 1
	s_cmp_ge_u32 s6, s11
	s_cselect_b32 s2, s20, s2
	s_and_b32 s3, s3, 7
	s_and_b32 s6, s7, -8
	s_lshl_b32 s35, s2, 4
	s_lshl_b32 s2, s34, 8
	s_or_b32 s36, s3, s6
	s_ashr_i32 s3, s2, 31
	s_lshl_b64 s[2:3], s[2:3], 11
	v_lshlrev_b32_e32 v2, 8, v1
	v_lshlrev_b32_e32 v1, 4, v1
	s_add_u32 s2, s31, s2
	v_and_b32_e32 v1, 0x70, v1
	s_movk_i32 s37, 0xf800
	v_mov_b32_e32 v239, 0
	s_addc_u32 s3, s33, s3
	v_and_or_b32 v238, v2, s37, v1
	v_lshl_add_u64 v[10:11], s[2:3], 0, v[238:239]
	s_mov_b32 s38, 0x60000
	v_add_co_u32_e32 v12, vcc, s38, v10
	s_lshl_b32 s6, s36, 8
	s_nop 0
	v_addc_co_u32_e32 v13, vcc, 0, v11, vcc
	s_mov_b32 s20, 0x40000
	s_ashr_i32 s7, s6, 31
	v_add_co_u32_e32 v14, vcc, s20, v10
	s_lshl_b64 s[6:7], s[6:7], 11
	s_nop 0
	v_addc_co_u32_e32 v15, vcc, 0, v11, vcc
	s_mov_b32 s39, 0x20000
	s_add_u32 s6, s29, s6
	v_add_co_u32_e32 v18, vcc, s39, v10
	s_addc_u32 s7, s30, s7
	s_nop 0
	v_addc_co_u32_e32 v19, vcc, 0, v11, vcc
	v_lshl_add_u64 v[30:31], s[6:7], 0, v[238:239]
	v_add_co_u32_e32 v32, vcc, s20, v30
	global_load_dwordx4 v[2:5], v[12:13], off
	global_load_dwordx4 v[6:9], v[14:15], off
	v_addc_co_u32_e32 v33, vcc, 0, v31, vcc
	v_add_co_u32_e32 v34, vcc, s39, v30
	global_load_dwordx4 v[10:13], v[18:19], off
	global_load_dwordx4 v[14:17], v238, s[2:3]
	v_addc_co_u32_e32 v35, vcc, 0, v31, vcc
	global_load_dwordx4 v[18:21], v[32:33], off
	global_load_dwordx4 v[22:25], v[34:35], off
	global_load_dwordx4 v[26:29], v238, s[6:7]
	v_add_co_u32_e32 v30, vcc, s38, v30
	v_mov_b32_e32 v1, v0
	s_nop 0
	v_addc_co_u32_e32 v31, vcc, 0, v31, vcc
	global_load_dwordx4 v[30:33], v[30:31], off
	s_movk_i32 s41, 0xf0
	v_ashrrev_i32_e32 v35, 4, v1
	v_xor_b32_e32 v1, v35, v1
	v_lshlrev_b32_e32 v35, 8, v35
	v_lshlrev_b32_e32 v1, 4, v1
	v_mov_b32_e32 v34, v0
	v_and_or_b32 v1, v1, s41, v35
	s_mov_b32 s40, 2
	s_movk_i32 s42, 0xff80
	s_mov_b32 s43, 0x10000
	s_mov_b32 s44, 0x11000
	s_movk_i32 s45, 0x1800
	s_movk_i32 s46, 0x1fff
	v_mov_b32_e32 v240, 0x8040
	s_mov_b32 s26, 2
	s_mov_b32 s47, s28
	s_mov_b32 s48, s34
	s_mov_b32 s49, s36
	v_mov_b32_e32 v83, v82
	v_mov_b32_e32 v84, v82
	v_mov_b32_e32 v85, v82
	v_mov_b32_e32 v102, v82
	v_mov_b32_e32 v103, v82
	v_mov_b32_e32 v104, v82
	v_mov_b32_e32 v105, v82
	v_mov_b32_e32 v106, v82
	v_mov_b32_e32 v107, v82
	v_mov_b32_e32 v108, v82
	v_mov_b32_e32 v109, v82
	v_mov_b32_e32 v110, v82
	v_mov_b32_e32 v111, v82
	s_waitcnt vmcnt(4)
	ds_write_b128 v1, v[14:17] offset:32768
	ds_write_b128 v1, v[10:13] offset:40960
	ds_write_b128 v1, v[6:9] offset:49152
	ds_write_b128 v1, v[2:5] offset:57344
	s_waitcnt vmcnt(1)
	ds_write_b128 v1, v[26:29]
	ds_write_b128 v1, v[22:25] offset:8192
	ds_write_b128 v1, v[18:21] offset:16384
	s_waitcnt vmcnt(0)
	ds_write_b128 v1, v[30:33] offset:24576
	v_mov_b32_e32 v112, v82
	v_lshlrev_b32_e32 v2, 4, v34
	v_lshlrev_b32_e32 v1, 8, v34
	v_and_b32_e32 v2, 0x70, v2
	v_and_or_b32 v238, v1, s37, v2
	v_lshl_add_u64 v[10:11], s[2:3], 0, v[238:239]
	v_add_co_u32_e32 v12, vcc, s38, v10
	v_lshl_add_u64 v[16:17], s[6:7], 0, v[238:239]
	s_nop 0
	v_addc_co_u32_e32 v13, vcc, 0, v11, vcc
	v_add_co_u32_e32 v14, vcc, s20, v10
	v_mov_b32_e32 v1, 0x10000
	s_nop 0
	v_addc_co_u32_e32 v15, vcc, 0, v11, vcc
	global_load_dwordx4 v[2:5], v[12:13], off offset:128
	global_load_dwordx4 v[6:9], v[14:15], off offset:128
	v_add_co_u32_e32 v14, vcc, s39, v10
	v_mov_b32_e32 v113, v82
	s_nop 0
	v_addc_co_u32_e32 v15, vcc, 0, v11, vcc
	v_add_co_u32_e32 v22, vcc, s38, v16
	v_mov_b32_e32 v114, v82
	s_nop 0
	v_addc_co_u32_e32 v23, vcc, 0, v17, vcc
	v_add_co_u32_e32 v34, vcc, s20, v16
	global_load_dwordx4 v[10:13], v[14:15], off offset:128
	global_load_dwordx4 v[18:21], v[22:23], off offset:128
	v_addc_co_u32_e32 v35, vcc, 0, v17, vcc
	v_add_co_u32_e32 v36, vcc, s39, v16
	v_mov_b32_e32 v115, v82
	s_nop 0
	v_addc_co_u32_e32 v37, vcc, 0, v17, vcc
	global_load_dwordx4 v[22:25], v[34:35], off offset:128
	global_load_dwordx4 v[26:29], v[36:37], off offset:128
	global_load_dwordx4 v[14:17], v238, s[2:3] offset:128
	global_load_dwordx4 v[30:33], v238, s[6:7] offset:128
	v_mov_b32_e32 v116, v82
	v_mov_b32_e32 v117, v82
	v_mov_b32_e32 v118, v82
	v_mov_b32_e32 v119, v82
	v_mov_b32_e32 v120, v82
	v_mov_b32_e32 v121, v82
	v_mov_b32_e32 v122, v82
	v_mov_b32_e32 v123, v82
	v_mov_b32_e32 v124, v82
	v_mov_b32_e32 v125, v82
	v_mov_b32_e32 v126, v82
	v_mov_b32_e32 v127, v82
	v_mov_b32_e32 v128, v82
	v_mov_b32_e32 v129, v82
	v_mov_b32_e32 v130, v82
	v_mov_b32_e32 v131, v82
	v_mov_b32_e32 v132, v82
	v_mov_b32_e32 v133, v82
	v_mov_b32_e32 v134, v82
	v_mov_b32_e32 v135, v82
	v_mov_b32_e32 v136, v82
	v_mov_b32_e32 v137, v82
	v_mov_b32_e32 v138, v82
	v_mov_b32_e32 v139, v82
	v_mov_b32_e32 v140, v82
	v_mov_b32_e32 v141, v82
	v_mov_b32_e32 v142, v82
	v_mov_b32_e32 v143, v82
	v_mov_b32_e32 v144, v82
	v_mov_b32_e32 v145, v82
	v_mov_b32_e32 v146, v82
	v_mov_b32_e32 v147, v82
	v_mov_b32_e32 v148, v82
	v_mov_b32_e32 v149, v82
	v_mov_b32_e32 v150, v82
	v_mov_b32_e32 v151, v82
	v_mov_b32_e32 v152, v82
	v_mov_b32_e32 v153, v82
	v_mov_b32_e32 v154, v82
	v_mov_b32_e32 v155, v82
	v_mov_b32_e32 v156, v82
	v_mov_b32_e32 v157, v82
	v_mov_b32_e32 v158, v82
	v_mov_b32_e32 v159, v82
	v_mov_b32_e32 v160, v82
	v_mov_b32_e32 v161, v82
	v_mov_b32_e32 v98, v82
	v_mov_b32_e32 v99, v82
	v_mov_b32_e32 v100, v82
	v_mov_b32_e32 v101, v82
	v_mov_b32_e32 v94, v82
	v_mov_b32_e32 v95, v82
	v_mov_b32_e32 v96, v82
	v_mov_b32_e32 v97, v82
	v_mov_b32_e32 v90, v82
	v_mov_b32_e32 v91, v82
	v_mov_b32_e32 v92, v82
	v_mov_b32_e32 v93, v82
	v_mov_b32_e32 v86, v82
	v_mov_b32_e32 v87, v82
	v_mov_b32_e32 v88, v82
	v_mov_b32_e32 v89, v82
	v_mov_b32_e32 v78, v82
	v_mov_b32_e32 v79, v82
	v_mov_b32_e32 v80, v82
	v_mov_b32_e32 v81, v82
	v_mov_b32_e32 v74, v82
	v_mov_b32_e32 v75, v82
	v_mov_b32_e32 v76, v82
	v_mov_b32_e32 v77, v82
	v_mov_b32_e32 v70, v82
	v_mov_b32_e32 v71, v82
	v_mov_b32_e32 v72, v82
	v_mov_b32_e32 v73, v82
	v_mov_b32_e32 v66, v82
	v_mov_b32_e32 v67, v82
	v_mov_b32_e32 v68, v82
	v_mov_b32_e32 v69, v82
	v_mov_b32_e32 v62, v82
	v_mov_b32_e32 v63, v82
	v_mov_b32_e32 v64, v82
	v_mov_b32_e32 v65, v82
	v_mov_b32_e32 v58, v82
	v_mov_b32_e32 v59, v82
	v_mov_b32_e32 v60, v82
	v_mov_b32_e32 v61, v82
	v_mov_b32_e32 v54, v82
	v_mov_b32_e32 v55, v82
	v_mov_b32_e32 v56, v82
	v_mov_b32_e32 v57, v82
	v_mov_b32_e32 v50, v82
	v_mov_b32_e32 v51, v82
	v_mov_b32_e32 v52, v82
	v_mov_b32_e32 v53, v82
	v_mov_b32_e32 v46, v82
	v_mov_b32_e32 v47, v82
	v_mov_b32_e32 v48, v82
	v_mov_b32_e32 v49, v82
	v_mov_b32_e32 v42, v82
	v_mov_b32_e32 v43, v82
	v_mov_b32_e32 v44, v82
	v_mov_b32_e32 v45, v82
	v_mov_b32_e32 v38, v82
	v_mov_b32_e32 v39, v82
	v_mov_b32_e32 v40, v82
	v_mov_b32_e32 v41, v82
	v_mov_b32_e32 v34, v82
	v_mov_b32_e32 v35, v82
	v_mov_b32_e32 v36, v82
	v_mov_b32_e32 v37, v82
	s_waitcnt lgkmcnt(0)
	s_barrier
	s_waitcnt vmcnt(0)
	s_branch .LBB0_2203

.Lbar_noinv_17:
	s_waitcnt lgkmcnt(0)
	s_barrier
.LBB0_2320:
	v_mov_b32_e32 v1, v0
	s_mov_b32 s2, s10
	s_waitcnt vmcnt(0)
	v_ashrrev_i32_e32 v2, 8, v1
	s_movk_i32 s3, 0x800
	v_lshl_add_u32 v1, s2, 1, v2
	v_cmp_gt_i32_e32 vcc, s3, v1
	s_and_saveexec_b64 s[8:9], vcc
	s_cbranch_execz .LBB0_2323
	s_load_dword s3, s[0:1], 0xe0
	s_load_dwordx4 s[4:7], s[16:17], 0xc8
	v_lshlrev_b32_e32 v2, 3, v2
	v_lshl_add_u32 v21, s2, 4, v2
	v_mbcnt_lo_u32_b32 v2, -1, 0
	s_waitcnt lgkmcnt(0)
	s_lshl_b32 s11, s3, 1
	s_add_u32 s20, s6, 0x4000
	s_addc_u32 s21, s7, 0
	v_mbcnt_hi_u32_b32 v30, -1, v2
	s_add_u32 s6, s6, 0x17f0000
	v_and_b32_e32 v2, 64, v30
	s_mov_b64 s[14:15], 0x4000
	s_addc_u32 s7, s7, 0
	s_lshl_b32 s27, s3, 4
	s_mov_b64 s[22:23], 0
	v_mov_b32_e32 v19, 0
	s_movk_i32 s30, 0x1800
	v_mov_b32_e32 v28, 0x9000
	s_movk_i32 s31, 0x1fff
	v_mov_b32_e32 v29, 0x7800
	s_movk_i32 s33, 0x1000
	v_add_u32_e32 v31, 64, v2
	v_xor_b32_e32 v32, 32, v30
	v_xor_b32_e32 v33, 16, v30
	v_xor_b32_e32 v34, 8, v30
	v_xor_b32_e32 v35, 4, v30
	v_xor_b32_e32 v36, 2, v30
	v_xor_b32_e32 v37, 1, v30
	s_mov_b64 s[24:25], 0x3000
	s_mov_b32 s26, 0x3a800000
	v_mov_b32_e32 v20, 0x358637bd
	s_mov_b32 s34, 0x800000
	s_movk_i32 s35, 0x7ff

.Lbar_noinv_18:
	s_waitcnt lgkmcnt(0)
	s_barrier
.LBB0_2381:
	s_mov_b32 s98, 0
	v_mov_b32_e32 v255, 0x0
	v_bfe_u32 v1, v0, 0, 1
	v_lshlrev_b32_e32 v1, 7, v1
	v_xor_b32_e32 v255, v255, v1
	v_bfe_u32 v1, v0, 1, 3
	v_mul_u32_u24_e32 v1, 0x110, v1
	v_xor_b32_e32 v255, v255, v1
	v_bfe_u32 v1, v0, 4, 2
	v_lshlrev_b32_e32 v1, 4, v1
	v_xor_b32_e32 v255, v255, v1
	v_bfe_u32 v1, v0, 8, 1
	v_lshlrev_b32_e32 v1, 14, v1
	v_xor_b32_e32 v255, v255, v1
	v_add_u32_e32 v254, 0x10000, v255
	v_xor_b32_e32 v253, 0x880, v255
	v_xor_b32_e32 v252, 0x10880, v255
	v_mov_b32_e32 v251, 0x8000
	v_bfe_u32 v1, v0, 0, 1
	v_lshlrev_b32_e32 v1, 7, v1
	v_xor_b32_e32 v251, v251, v1
	v_bfe_u32 v1, v0, 1, 3
	v_mul_u32_u24_e32 v1, 0x110, v1
	v_xor_b32_e32 v251, v251, v1
	v_bfe_u32 v1, v0, 4, 2
	v_lshlrev_b32_e32 v1, 4, v1
	v_xor_b32_e32 v251, v251, v1
	v_bfe_u32 v1, v0, 6, 2
	v_lshlrev_b32_e32 v1, 13, v1
	v_xor_b32_e32 v251, v251, v1
	v_add_u32_e32 v250, 0x10000, v251
	v_xor_b32_e32 v249, 0x880, v251
	v_xor_b32_e32 v248, 0x10880, v251
	v_xor_b32_e32 v247, 0x40, v255
	v_xor_b32_e32 v246, 0x10040, v255
	v_xor_b32_e32 v245, 0x8c0, v255
	v_xor_b32_e32 v244, 0x108c0, v255
	v_xor_b32_e32 v243, 0x40, v251
	v_xor_b32_e32 v242, 0x10040, v251
	v_xor_b32_e32 v241, 0x8c0, v251
	v_xor_b32_e32 v237, 0x108c0, v251
	v_mov_b32_e32 v236, 0x0
	v_bfe_u32 v1, v0, 0, 4
	v_lshlrev_b32_e32 v1, 4, v1
	v_xor_b32_e32 v236, v236, v1
	v_bfe_u32 v1, v0, 4, 4
	v_mul_u32_u24_e32 v1, 0x110, v1
	v_xor_b32_e32 v236, v236, v1
	v_bfe_u32 v1, v0, 8, 1
	v_lshlrev_b32_e32 v1, 12, v1
	v_xor_b32_e32 v236, v236, v1
	v_add_u32_e32 v235, 0x10000, v236
	v_mov_b32_e32 v234, 0x0
	v_bfe_u32 v1, v0, 0, 3
	v_lshlrev_b32_e32 v1, 4, v1
	v_add_u32_e32 v234, v234, v1
	v_bfe_u32 v1, v0, 3, 6
	v_lshlrev_b32_e32 v1, 11, v1
	v_add_u32_e32 v234, v234, v1
	v_add_u32_e32 v233, 0x20000, v234
	v_add_u32_e32 v232, 0x40000, v234
	v_add_u32_e32 v231, 0x60000, v234
	v_mov_b32_e32 v1, v0
	s_mov_b32 s2, s10
	s_load_dword s8, s[0:1], 0xe0
	s_load_dwordx2 s[2:3], s[16:17], 0xd0
	s_waitcnt vmcnt(0)
	v_mov_b32_e32 v2, v0
	s_mov_b32 s27, 0
	s_waitcnt lgkmcnt(0)
	s_add_u32 s11, s2, 0x17f0000
	s_addc_u32 s24, s3, 0
	s_add_u32 s6, s2, 0x37f0000
	s_addc_u32 s7, s3, 0
	s_add_u32 s25, s2, 0x770000
	s_addc_u32 s26, s3, 0
	s_lshr_b32 s28, s8, 3
	v_cvt_f32_u32_e32 v1, s28
	s_sub_i32 s8, 0, s28
	s_mov_b32 s2, s10
	v_rcp_iflag_f32_e32 v1, v1
	s_ashr_i32 s3, s2, 3
	s_abs_i32 s3, s3
	s_ashr_i32 s2, s2, 31
	v_mul_f32_e32 v1, 0x4f7ffffe, v1
	v_cvt_u32_f32_e32 v1, v1
	s_nop 0
	v_readfirstlane_b32 s30, v1
	s_mul_i32 s8, s8, s30
	s_mul_hi_u32 s8, s30, s8
	s_add_i32 s30, s30, s8
	s_mul_hi_u32 s8, s3, s30
	s_mul_i32 s8, s8, s28
	s_sub_i32 s3, s3, s8
	s_sub_i32 s8, s3, s28
	s_cmp_ge_u32 s3, s28
	s_cselect_b32 s3, s8, s3
	s_sub_i32 s8, s3, s28
	s_cmp_ge_u32 s3, s28
	s_cselect_b32 s3, s8, s3
	s_xor_b32 s3, s3, s2
	s_sub_i32 s31, s3, s2
	s_mul_hi_u32 s3, s30, 0xb0
	s_mul_i32 s3, s3, s28
	s_sub_i32 s3, 0xb0, s3
	s_sub_i32 s8, s3, s28
	s_cmp_ge_u32 s3, s28
	s_cselect_b32 s3, s8, s3
	s_sub_i32 s8, s3, s28
	s_cmp_ge_u32 s3, s28
	s_cselect_b32 s29, s8, s3
	s_sub_i32 s33, 0xb0, s29
	s_mov_b32 s2, s10
	s_cmp_ge_i32 s31, s33
	s_cbranch_scc1 .LBB0_2430
	s_mov_b32 s9, s10
	s_cmpk_gt_i32 s31, 0x9f
	s_cbranch_scc0 .LBB0_2384
	s_lshl_b32 s2, s31, 2
	s_add_i32 s2, s2, 0x7ffffd80
	s_and_b32 s8, s2, 0x7ffffff8
	s_and_b32 s2, s31, 1
	s_or_b32 s34, s2, 20
	s_cbranch_execz .LBB0_2385
	s_branch .LBB0_2386

.Lbar_noinv_19:
	s_waitcnt lgkmcnt(0)
	s_barrier
.LBB0_2541:
	s_mov_b32 s98, 0
	v_mov_b32_e32 v255, 0x0
	v_bfe_u32 v1, v0, 0, 1
	v_lshlrev_b32_e32 v1, 7, v1
	v_xor_b32_e32 v255, v255, v1
	v_bfe_u32 v1, v0, 1, 3
	v_mul_u32_u24_e32 v1, 0x110, v1
	v_xor_b32_e32 v255, v255, v1
	v_bfe_u32 v1, v0, 4, 2
	v_lshlrev_b32_e32 v1, 4, v1
	v_xor_b32_e32 v255, v255, v1
	v_bfe_u32 v1, v0, 8, 1
	v_lshlrev_b32_e32 v1, 14, v1
	v_xor_b32_e32 v255, v255, v1
	v_add_u32_e32 v254, 0x10000, v255
	v_xor_b32_e32 v253, 0x880, v255
	v_xor_b32_e32 v252, 0x10880, v255
	v_mov_b32_e32 v251, 0x8000
	v_bfe_u32 v1, v0, 0, 1
	v_lshlrev_b32_e32 v1, 7, v1
	v_xor_b32_e32 v251, v251, v1
	v_bfe_u32 v1, v0, 1, 3
	v_mul_u32_u24_e32 v1, 0x110, v1
	v_xor_b32_e32 v251, v251, v1
	v_bfe_u32 v1, v0, 4, 2
	v_lshlrev_b32_e32 v1, 4, v1
	v_xor_b32_e32 v251, v251, v1
	v_bfe_u32 v1, v0, 6, 2
	v_lshlrev_b32_e32 v1, 13, v1
	v_xor_b32_e32 v251, v251, v1
	v_add_u32_e32 v250, 0x10000, v251
	v_xor_b32_e32 v249, 0x880, v251
	v_xor_b32_e32 v248, 0x10880, v251
	v_xor_b32_e32 v247, 0x40, v255
	v_xor_b32_e32 v246, 0x10040, v255
	v_xor_b32_e32 v245, 0x8c0, v255
	v_xor_b32_e32 v244, 0x108c0, v255
	v_xor_b32_e32 v243, 0x40, v251
	v_xor_b32_e32 v242, 0x10040, v251
	v_xor_b32_e32 v241, 0x8c0, v251
	v_xor_b32_e32 v237, 0x108c0, v251
	v_mov_b32_e32 v236, 0x0
	v_bfe_u32 v1, v0, 0, 4
	v_lshlrev_b32_e32 v1, 4, v1
	v_xor_b32_e32 v236, v236, v1
	v_bfe_u32 v1, v0, 4, 4
	v_mul_u32_u24_e32 v1, 0x110, v1
	v_xor_b32_e32 v236, v236, v1
	v_bfe_u32 v1, v0, 8, 1
	v_lshlrev_b32_e32 v1, 12, v1
	v_xor_b32_e32 v236, v236, v1
	v_add_u32_e32 v235, 0x10000, v236
	v_mov_b32_e32 v234, 0x0
	v_bfe_u32 v1, v0, 0, 3
	v_lshlrev_b32_e32 v1, 4, v1
	v_add_u32_e32 v234, v234, v1
	v_bfe_u32 v1, v0, 3, 6
	v_mul_u32_u24_e32 v1, 0x1600, v1
	v_add_u32_e32 v234, v234, v1
	v_add_u32_e32 v233, 0x58000, v234
	v_add_u32_e32 v232, 0xb0000, v234
	v_add_u32_e32 v231, 0x108000, v234
	v_mov_b32_e32 v1, v0
	s_load_dword s0, s[0:1], 0xe0
	s_mov_b32 s1, s10
	v_mov_b32_e32 v1, v0
	s_waitcnt lgkmcnt(0)
	s_lshr_b32 s11, s0, 3
	s_waitcnt vmcnt(0)
	v_cvt_f32_u32_e32 v2, s11
	s_mov_b32 s0, s10
	s_ashr_i32 s1, s0, 3
	v_rcp_iflag_f32_e32 v2, v2
	s_ashr_i32 s2, s0, 31
	s_sub_i32 s0, 0, s11
	s_abs_i32 s1, s1
	v_mul_f32_e32 v1, 0x4f7ffffe, v2
	v_cvt_u32_f32_e32 v1, v1
	s_mov_b32 s42, 0
	v_readfirstlane_b32 s3, v1
	s_mul_i32 s0, s0, s3
	s_mul_hi_u32 s0, s3, s0
	s_add_i32 s0, s3, s0
	s_mul_hi_u32 s3, s1, s0
	s_mul_i32 s3, s3, s11
	s_sub_i32 s1, s1, s3
	s_sub_i32 s3, s1, s11
	s_cmp_ge_u32 s1, s11
	s_cselect_b32 s1, s3, s1
	s_sub_i32 s3, s1, s11
	s_cmp_ge_u32 s1, s11
	s_cselect_b32 s1, s3, s1
	s_xor_b32 s1, s1, s2
	s_sub_i32 s20, s1, s2
	s_mov_b32 s1, s10
	s_cmp_gt_i32 s20, 31
	s_cbranch_scc1 .LBB0_2605
	s_load_dwordx4 s[4:7], s[16:17], 0xc8
	s_mov_b32 s1, s10
	v_mov_b32_e32 v82, 0
	v_mov_b32_e32 v1, v0
	s_waitcnt lgkmcnt(0)
	s_add_u32 s2, s4, 0x2000000
	s_addc_u32 s3, s5, 0
	s_add_u32 s8, s6, 0x27000
	s_addc_u32 s9, s7, 0
	s_add_u32 s21, s6, 0x37f0000
	s_addc_u32 s22, s7, 0
	s_add_u32 s23, s6, 0x1270000
	s_addc_u32 s24, s7, 0
	s_ashr_i32 s6, s20, 31
	s_lshr_b32 s6, s6, 27
	s_add_i32 s6, s20, s6
	s_ashr_i32 s6, s6, 5
	s_lshl_b32 s7, s20, 1
	s_lshl_b32 s12, s6, 6
	s_sub_i32 s7, s7, s12
	s_lshl_b32 s6, s6, 2
	s_and_b32 s12, s20, 3
	s_or_b32 s25, s6, s12
	s_sub_i32 s6, s11, s20
	s_add_i32 s6, s6, 31
	s_mul_hi_u32 s0, s6, s0
	s_mul_i32 s12, s0, s11
	s_sub_i32 s6, s6, s12
	s_add_i32 s12, s0, 1
	s_sub_i32 s13, s6, s11
	s_cmp_ge_u32 s6, s11
	s_cselect_b32 s0, s12, s0
	s_cselect_b32 s6, s13, s6
	s_add_i32 s12, s0, 1
	s_cmp_ge_u32 s6, s11
	s_cselect_b32 s33, s12, s0
	s_and_b32 s0, s1, 7
	s_and_b32 s1, s7, -8
	s_movk_i32 s26, 0xb00
	v_lshrrev_b32_e32 v2, 3, v1
	s_or_b32 s27, s0, s1
	s_lshl_b32 s0, s25, 8
	s_mul_i32 s1, s25, 0x160000
	v_mul_lo_u32 v2, v2, s26
	v_lshlrev_b32_e32 v1, 3, v1
	s_mul_hi_i32 s6, s0, 0x1600
	s_add_u32 s0, s23, s1
	v_and_or_b32 v1, v1, 56, v2
	v_mov_b32_e32 v239, 0
	s_addc_u32 s1, s24, s6
	v_lshlrev_b32_e32 v238, 1, v1
	v_lshl_add_u64 v[2:3], s[0:1], 0, v[238:239]
	s_mov_b32 s28, 0x108000
	v_add_co_u32_e32 v34, vcc, s28, v2
	s_mov_b32 s12, 0xb0000
	s_nop 0
	v_addc_co_u32_e32 v35, vcc, 0, v3, vcc
	v_add_co_u32_e32 v36, vcc, s12, v2
	s_lshl_b32 s6, s27, 8
	s_mul_i32 s7, s27, 0x160000
	v_addc_co_u32_e32 v37, vcc, 0, v3, vcc
	s_mov_b32 s29, 0x58000
	s_mul_hi_i32 s13, s6, 0x1600
	s_add_u32 s6, s21, s7
	v_add_co_u32_e32 v2, vcc, s29, v2
	s_addc_u32 s7, s22, s13
	s_nop 0
	v_addc_co_u32_e32 v3, vcc, 0, v3, vcc
	v_lshl_add_u64 v[22:23], s[6:7], 0, v[238:239]
	v_add_co_u32_e32 v24, vcc, s12, v22
	global_load_dwordx4 v[2:5], v[2:3], off
	s_nop 0
	v_addc_co_u32_e32 v25, vcc, 0, v23, vcc
	v_add_co_u32_e32 v26, vcc, s29, v22
	v_mov_b32_e32 v1, v0
	s_nop 0
	v_addc_co_u32_e32 v27, vcc, 0, v23, vcc
	v_add_co_u32_e32 v38, vcc, s28, v22
	global_load_dwordx4 v[6:9], v[24:25], off
	global_load_dwordx4 v[10:13], v[26:27], off
	global_load_dwordx4 v[14:17], v238, s[0:1]
	global_load_dwordx4 v[18:21], v238, s[6:7]
	v_addc_co_u32_e32 v39, vcc, 0, v23, vcc
	global_load_dwordx4 v[22:25], v[38:39], off
	global_load_dwordx4 v[26:29], v[36:37], off
	global_load_dwordx4 v[30:33], v[34:35], off
	s_movk_i32 s31, 0xf0
	v_ashrrev_i32_e32 v34, 4, v1
	v_xor_b32_e32 v1, v34, v1
	v_lshlrev_b32_e32 v34, 8, v34
	v_lshlrev_b32_e32 v1, 4, v1
	v_and_or_b32 v1, v1, s31, v34
	s_mov_b32 s30, 2
	s_mul_i32 s33, s33, 44
	s_movk_i32 s34, 0xff80
	s_mov_b32 s35, 0x10000
	s_mov_b32 s36, 0x11000
	s_movk_i32 s37, 0x1800
	s_movk_i32 s38, 0x1fff
	v_mov_b32_e32 v240, 0x8040
	s_mov_b32 s18, 2
	s_mov_b32 s39, s20
	s_mov_b32 s40, s25
	s_mov_b32 s41, s27
	v_mov_b32_e32 v83, v82
	v_mov_b32_e32 v84, v82
	v_mov_b32_e32 v85, v82
	v_mov_b32_e32 v102, v82
	v_mov_b32_e32 v103, v82
	v_mov_b32_e32 v104, v82
	v_mov_b32_e32 v105, v82
	v_mov_b32_e32 v106, v82
	v_mov_b32_e32 v107, v82
	v_mov_b32_e32 v108, v82
	v_mov_b32_e32 v109, v82
	v_mov_b32_e32 v110, v82
	v_mov_b32_e32 v111, v82
	v_mov_b32_e32 v112, v82
	v_mov_b32_e32 v113, v82
	s_waitcnt vmcnt(4)
	ds_write_b128 v1, v[14:17] offset:32768
	s_waitcnt vmcnt(3)
	ds_write_b128 v1, v[18:21]
	ds_write_b128 v1, v[2:5] offset:40960
	ds_write_b128 v1, v[10:13] offset:8192
	ds_write_b128 v1, v[6:9] offset:16384
	s_waitcnt vmcnt(2)
	ds_write_b128 v1, v[22:25] offset:24576
	s_waitcnt vmcnt(1)
	ds_write_b128 v1, v[26:29] offset:49152
	s_waitcnt vmcnt(0)
	ds_write_b128 v1, v[30:33] offset:57344
	v_mov_b32_e32 v1, v0
	v_mov_b32_e32 v114, v82
	v_lshrrev_b32_e32 v2, 3, v1
	v_mul_lo_u32 v2, v2, s26
	v_lshlrev_b32_e32 v1, 3, v1
	v_and_or_b32 v1, v1, 56, v2
	v_lshlrev_b32_e32 v238, 1, v1
	v_lshl_add_u64 v[10:11], s[0:1], 0, v[238:239]
	v_add_co_u32_e32 v12, vcc, s28, v10
	v_lshl_add_u64 v[16:17], s[6:7], 0, v[238:239]
	s_nop 0
	v_addc_co_u32_e32 v13, vcc, 0, v11, vcc
	v_add_co_u32_e32 v14, vcc, s12, v10
	v_mov_b32_e32 v1, 0x10000
	s_nop 0
	v_addc_co_u32_e32 v15, vcc, 0, v11, vcc
	global_load_dwordx4 v[2:5], v[12:13], off offset:128
	global_load_dwordx4 v[6:9], v[14:15], off offset:128
	v_add_co_u32_e32 v14, vcc, s29, v10
	v_mov_b32_e32 v115, v82
	s_nop 0
	v_addc_co_u32_e32 v15, vcc, 0, v11, vcc
	v_add_co_u32_e32 v22, vcc, s28, v16
	v_mov_b32_e32 v116, v82
	s_nop 0
	v_addc_co_u32_e32 v23, vcc, 0, v17, vcc
	v_add_co_u32_e32 v34, vcc, s12, v16
	global_load_dwordx4 v[10:13], v[14:15], off offset:128
	global_load_dwordx4 v[18:21], v[22:23], off offset:128
	v_addc_co_u32_e32 v35, vcc, 0, v17, vcc
	v_add_co_u32_e32 v36, vcc, s29, v16
	v_mov_b32_e32 v117, v82
	s_nop 0
	v_addc_co_u32_e32 v37, vcc, 0, v17, vcc
	global_load_dwordx4 v[22:25], v[34:35], off offset:128
	global_load_dwordx4 v[26:29], v[36:37], off offset:128
	global_load_dwordx4 v[14:17], v238, s[0:1] offset:128
	global_load_dwordx4 v[30:33], v238, s[6:7] offset:128
	v_mov_b32_e32 v118, v82
	v_mov_b32_e32 v119, v82
	v_mov_b32_e32 v120, v82
	v_mov_b32_e32 v121, v82
	v_mov_b32_e32 v122, v82
	v_mov_b32_e32 v123, v82
	v_mov_b32_e32 v124, v82
	v_mov_b32_e32 v125, v82
	v_mov_b32_e32 v126, v82
	v_mov_b32_e32 v127, v82
	v_mov_b32_e32 v128, v82
	v_mov_b32_e32 v129, v82
	v_mov_b32_e32 v130, v82
	v_mov_b32_e32 v131, v82
	v_mov_b32_e32 v132, v82
	v_mov_b32_e32 v133, v82
	v_mov_b32_e32 v134, v82
	v_mov_b32_e32 v135, v82
	v_mov_b32_e32 v136, v82
	v_mov_b32_e32 v137, v82
	v_mov_b32_e32 v138, v82
	v_mov_b32_e32 v139, v82
	v_mov_b32_e32 v140, v82
	v_mov_b32_e32 v141, v82
	v_mov_b32_e32 v142, v82
	v_mov_b32_e32 v143, v82
	v_mov_b32_e32 v144, v82
	v_mov_b32_e32 v145, v82
	v_mov_b32_e32 v146, v82
	v_mov_b32_e32 v147, v82
	v_mov_b32_e32 v148, v82
	v_mov_b32_e32 v149, v82
	v_mov_b32_e32 v150, v82
	v_mov_b32_e32 v151, v82
	v_mov_b32_e32 v152, v82
	v_mov_b32_e32 v153, v82
	v_mov_b32_e32 v154, v82
	v_mov_b32_e32 v155, v82
	v_mov_b32_e32 v156, v82
	v_mov_b32_e32 v157, v82
	v_mov_b32_e32 v158, v82
	v_mov_b32_e32 v159, v82
	v_mov_b32_e32 v160, v82
	v_mov_b32_e32 v161, v82
	v_mov_b32_e32 v98, v82
	v_mov_b32_e32 v99, v82
	v_mov_b32_e32 v100, v82
	v_mov_b32_e32 v101, v82
	v_mov_b32_e32 v94, v82
	v_mov_b32_e32 v95, v82
	v_mov_b32_e32 v96, v82
	v_mov_b32_e32 v97, v82
	v_mov_b32_e32 v90, v82
	v_mov_b32_e32 v91, v82
	v_mov_b32_e32 v92, v82
	v_mov_b32_e32 v93, v82
	v_mov_b32_e32 v86, v82
	v_mov_b32_e32 v87, v82
	v_mov_b32_e32 v88, v82
	v_mov_b32_e32 v89, v82
	v_mov_b32_e32 v78, v82
	v_mov_b32_e32 v79, v82
	v_mov_b32_e32 v80, v82
	v_mov_b32_e32 v81, v82
	v_mov_b32_e32 v74, v82
	v_mov_b32_e32 v75, v82
	v_mov_b32_e32 v76, v82
	v_mov_b32_e32 v77, v82
	v_mov_b32_e32 v70, v82
	v_mov_b32_e32 v71, v82
	v_mov_b32_e32 v72, v82
	v_mov_b32_e32 v73, v82
	v_mov_b32_e32 v66, v82
	v_mov_b32_e32 v67, v82
	v_mov_b32_e32 v68, v82
	v_mov_b32_e32 v69, v82
	v_mov_b32_e32 v62, v82
	v_mov_b32_e32 v63, v82
	v_mov_b32_e32 v64, v82
	v_mov_b32_e32 v65, v82
	v_mov_b32_e32 v58, v82
	v_mov_b32_e32 v59, v82
	v_mov_b32_e32 v60, v82
	v_mov_b32_e32 v61, v82
	v_mov_b32_e32 v54, v82
	v_mov_b32_e32 v55, v82
	v_mov_b32_e32 v56, v82
	v_mov_b32_e32 v57, v82
	v_mov_b32_e32 v50, v82
	v_mov_b32_e32 v51, v82
	v_mov_b32_e32 v52, v82
	v_mov_b32_e32 v53, v82
	v_mov_b32_e32 v46, v82
	v_mov_b32_e32 v47, v82
	v_mov_b32_e32 v48, v82
	v_mov_b32_e32 v49, v82
	v_mov_b32_e32 v42, v82
	v_mov_b32_e32 v43, v82
	v_mov_b32_e32 v44, v82
	v_mov_b32_e32 v45, v82
	v_mov_b32_e32 v38, v82
	v_mov_b32_e32 v39, v82
	v_mov_b32_e32 v40, v82
	v_mov_b32_e32 v41, v82
	v_mov_b32_e32 v34, v82
	v_mov_b32_e32 v35, v82
	v_mov_b32_e32 v36, v82
	v_mov_b32_e32 v37, v82
	s_waitcnt lgkmcnt(0)
	s_barrier
	s_waitcnt vmcnt(0)
	s_branch .LBB0_2545
